# nt on the other read-once streams: LayerNorm residual loads (x, x1, x2 last reads) and P0's f32 input loads
# speedup vs baseline: 1.0329x; 1.0124x over previous
; #define LAS __attribute__((address_space(3)))
; __device__ __forceinline__ void p0_transpose_item(const float* W0, const float* W1, int K, int Nsrc, int Nd, int mode, bf16* WT, LAS float* scr, int item, int lane) {
;     const int nblk = Nd / 32, kb = item / nblk, nb = item % nblk, k0 = 64 * kb, n0 = 32 * nb;
;     const float* src = W0; int c0 = n0;
;     if (mode == 1) { const int t = n0 / 256, w = n0 % 256; src = (w < 128) ? W0 : W1; c0 = t * 128 + (w & 127); }
;     const bool okc = (c0 + (lane & 31)) < Nsrc; const int cc = okc ? c0 + (lane & 31) : Nsrc - 1;
;     float tv[32];
; #pragma unroll
;     for (int i = 0; i < 32; ++i) { const int kk = 2 * i + (lane >> 5); tv[i] = src[(size_t)(k0 + kk) * Nsrc + cc]; }
; #pragma unroll
;     for (int i = 0; i < 32; ++i) { const int kk = 2 * i + (lane >> 5); scr[kk * 33 + (lane & 31)] = okc ? tv[i] : 0.f; }
.LBB0_8:
	s_mul_hi_i32 s7, s6, 0x2e8ba2e9
	s_lshr_b32 s10, s7, 31
	s_ashr_i32 s7, s7, 5
	s_add_i32 s7, s7, s10
	s_mul_i32 s10, s7, 0xffffff50
	s_mul_i32 s12, s7, 0xffffea00
	s_add_i32 s11, s6, s10
	s_add_i32 s10, s2, s12
	s_bfe_u32 s12, s11, 0x3001c
	s_lshr_b32 s13, s10, 23
	s_add_i32 s11, s11, s12
	s_and_b32 s12, s13, 0xff
	s_add_i32 s12, s10, s12
	s_and_b32 s12, s12, 0xff00
	v_add_u32_e32 v12, s10, v170
	s_sub_i32 s10, s10, s12
	s_sext_i32_i16 s12, s10
	s_sext_i32_i16 s11, s11
	s_cmpk_lt_i32 s12, 0x80
	s_waitcnt lgkmcnt(0)
	s_cselect_b32 s12, s19, s21
	s_cselect_b32 s13, s18, s20
	s_lshl_b32 s11, s11, 4
	s_and_b32 s14, s10, 0x60
	s_lshl_b32 s10, s7, 6
	s_and_b32 s7, s11, 0xffffff80
	v_ashrrev_i32_e32 v13, 31, v12
	s_ashr_i32 s11, s10, 31
	s_or_b32 s7, s7, s14
	v_add_u32_e32 v14, 8, v12
	v_add_u32_e32 v16, 16, v12
	v_add_u32_e32 v18, 24, v12
	v_lshlrev_b64 v[12:13], 11, v[12:13]
	v_lshl_add_u64 v[22:23], s[10:11], 1, v[2:3]
	v_or_b32_e32 v87, s7, v168
	v_lshl_add_u64 v[28:29], v[22:23], 0, v[12:13]
	v_min_i32_e32 v12, 0xaff, v87
	v_mov_b32_e32 v20, s13
	v_mov_b32_e32 v21, s12
	v_or_b32_e32 v24, s10, v169
	v_ashrrev_i32_e32 v13, 31, v12
	v_or_b32_e32 v25, 2, v24
	v_or_b32_e32 v26, 4, v24
	v_or_b32_e32 v30, 6, v24
	v_or_b32_e32 v32, 8, v24
	v_or_b32_e32 v34, 10, v24
	v_or_b32_e32 v36, 12, v24
	v_or_b32_e32 v38, 14, v24
	v_or_b32_e32 v40, 16, v24
	v_or_b32_e32 v42, 18, v24
	v_or_b32_e32 v44, 20, v24
	v_or_b32_e32 v46, 22, v24
	v_or_b32_e32 v48, 24, v24
	v_or_b32_e32 v50, 26, v24
	v_or_b32_e32 v52, 28, v24
	v_or_b32_e32 v54, 30, v24
	v_or_b32_e32 v56, 32, v24
	v_or_b32_e32 v58, 34, v24
	v_or_b32_e32 v60, 36, v24
	v_or_b32_e32 v62, 38, v24
	v_or_b32_e32 v64, 40, v24
	v_or_b32_e32 v66, 42, v24
	v_or_b32_e32 v68, 44, v24
	v_or_b32_e32 v70, 46, v24
	v_or_b32_e32 v72, 48, v24
	v_or_b32_e32 v74, 50, v24
	v_or_b32_e32 v76, 52, v24
	v_or_b32_e32 v78, 54, v24
	v_or_b32_e32 v80, 56, v24
	v_or_b32_e32 v82, 58, v24
	v_or_b32_e32 v84, 60, v24
	v_or_b32_e32 v86, 62, v24
	v_lshl_add_u64 v[12:13], v[12:13], 2, v[20:21]
	v_mad_i64_i32 v[20:21], s[10:11], v24, s4, v[12:13]
	v_mad_i64_i32 v[24:25], s[10:11], v25, s4, v[12:13]
	v_mad_i64_i32 v[26:27], s[10:11], v26, s4, v[12:13]
	v_mad_i64_i32 v[30:31], s[10:11], v30, s4, v[12:13]
	v_mad_i64_i32 v[32:33], s[10:11], v32, s4, v[12:13]
	v_mad_i64_i32 v[34:35], s[10:11], v34, s4, v[12:13]
	v_mad_i64_i32 v[36:37], s[10:11], v36, s4, v[12:13]
	v_mad_i64_i32 v[38:39], s[10:11], v38, s4, v[12:13]
	v_mad_i64_i32 v[40:41], s[10:11], v40, s4, v[12:13]
	v_mad_i64_i32 v[42:43], s[10:11], v42, s4, v[12:13]
	v_mad_i64_i32 v[44:45], s[10:11], v44, s4, v[12:13]
	v_mad_i64_i32 v[46:47], s[10:11], v46, s4, v[12:13]
	v_mad_i64_i32 v[48:49], s[10:11], v48, s4, v[12:13]
	v_mad_i64_i32 v[50:51], s[10:11], v50, s4, v[12:13]
	v_mad_i64_i32 v[52:53], s[10:11], v52, s4, v[12:13]
	v_mad_i64_i32 v[54:55], s[10:11], v54, s4, v[12:13]
	v_mad_i64_i32 v[56:57], s[10:11], v56, s4, v[12:13]
	v_mad_i64_i32 v[58:59], s[10:11], v58, s4, v[12:13]
	v_mad_i64_i32 v[60:61], s[10:11], v60, s4, v[12:13]
	v_mad_i64_i32 v[62:63], s[10:11], v62, s4, v[12:13]
	v_mad_i64_i32 v[64:65], s[10:11], v64, s4, v[12:13]
	v_mad_i64_i32 v[66:67], s[10:11], v66, s4, v[12:13]
	v_mad_i64_i32 v[68:69], s[10:11], v68, s4, v[12:13]
	v_mad_i64_i32 v[70:71], s[10:11], v70, s4, v[12:13]
	v_mad_i64_i32 v[72:73], s[10:11], v72, s4, v[12:13]
	v_mad_i64_i32 v[74:75], s[10:11], v74, s4, v[12:13]
	v_mad_i64_i32 v[76:77], s[10:11], v76, s4, v[12:13]
	v_mad_i64_i32 v[78:79], s[10:11], v78, s4, v[12:13]
	v_mad_i64_i32 v[80:81], s[10:11], v80, s4, v[12:13]
	v_mad_i64_i32 v[82:83], s[10:11], v82, s4, v[12:13]
	v_mad_i64_i32 v[84:85], s[10:11], v84, s4, v[12:13]
	v_mad_i64_i32 v[12:13], s[10:11], v86, s4, v[12:13]
	global_load_dword v20, v[20:21], off nt
	s_nop 0
	global_load_dword v21, v[24:25], off nt
	s_nop 0
	global_load_dword v24, v[26:27], off nt
	global_load_dword v25, v[30:31], off nt
	s_nop 0
	global_load_dword v26, v[32:33], off nt
	global_load_dword v27, v[34:35], off nt
	s_nop 0
	global_load_dword v36, v[36:37], off nt
	s_nop 0
	global_load_dword v37, v[38:39], off nt
	s_nop 0
	global_load_dword v38, v[40:41], off nt
	global_load_dword v39, v[42:43], off nt
	s_nop 0
	global_load_dword v40, v[44:45], off nt
	global_load_dword v41, v[46:47], off nt
	global_load_dword v42, v[48:49], off nt
	global_load_dword v43, v[50:51], off nt
	s_nop 0
	global_load_dword v44, v[52:53], off nt
	global_load_dword v45, v[54:55], off nt
	global_load_dword v46, v[56:57], off nt
	global_load_dword v47, v[58:59], off nt
	global_load_dword v48, v[60:61], off nt
	global_load_dword v49, v[62:63], off nt
	global_load_dword v50, v[64:65], off nt
	global_load_dword v51, v[66:67], off nt
	global_load_dword v52, v[68:69], off nt
	global_load_dword v53, v[70:71], off nt
	global_load_dword v54, v[72:73], off nt
	global_load_dword v55, v[74:75], off nt
	global_load_dword v56, v[76:77], off nt
	global_load_dword v57, v[78:79], off nt
	global_load_dword v58, v[80:81], off nt
	global_load_dword v59, v[82:83], off nt
	global_load_dword v60, v[84:85], off nt
	s_nop 0
	global_load_dword v12, v[12:13], off nt
	v_ashrrev_i32_e32 v15, 31, v14
	v_ashrrev_i32_e32 v17, 31, v16
	v_ashrrev_i32_e32 v19, 31, v18
	v_lshlrev_b64 v[14:15], 11, v[14:15]
	v_cmp_gt_i32_e32 vcc, s5, v87
	v_lshlrev_b64 v[16:17], 11, v[16:17]
	v_lshlrev_b64 v[18:19], 11, v[18:19]
	v_lshl_add_u64 v[30:31], v[22:23], 0, v[14:15]
	v_lshl_add_u64 v[32:33], v[22:23], 0, v[16:17]
	v_lshl_add_u64 v[34:35], v[22:23], 0, v[18:19]
	s_add_i32 s6, s6, s79
	s_add_i32 s2, s2, s3
	s_cmpk_lt_i32 s6, 0xb00
	s_waitcnt vmcnt(31)
; #define GAS __attribute__((address_space(1)))
; #define LAS __attribute__((address_space(3)))
; #define LDS_WAIT() asm volatile("s_waitcnt lgkmcnt(0)" ::: "memory")
; __device__ __forceinline__ unsigned pk2(float lo, float hi) { f32x2_p v = {lo, hi}; bf16x2_p b = __builtin_convertvector(v, bf16x2_p); return __builtin_bit_cast(unsigned, b); }
; __device__ __forceinline__ void p0_transpose_item(const float* W0, const float* W1, int K, int Nsrc, int Nd, int mode, bf16* WT, LAS float* scr, int item, int lane) {
;     ...
;     for (int i = 0; i < 32; ++i) { const int kk = 2 * i + (lane >> 5); scr[kk * 33 + (lane & 31)] = okc ? tv[i] : 0.f; }
;     LDS_WAIT(); asm volatile("" ::: "memory");
;     const int c = lane & 7;
; #pragma unroll
;     for (int j = 0; j < 4; ++j) { const int n = (lane >> 3) + 8 * j; const LAS float* s = scr + (8 * c) * 33 + n;
;         v4u o; o.x = pk2(s[0 * 33], s[1 * 33]); o.y = pk2(s[2 * 33], s[3 * 33]); o.z = pk2(s[4 * 33], s[5 * 33]); o.w = pk2(s[6 * 33], s[7 * 33]);
;         *(GAS v4u*)(WT + (size_t)(n0 + n) * K + k0 + 8 * c) = o; }
	v_cndmask_b32_e32 v13, 0, v20, vcc
	s_waitcnt vmcnt(30)
	v_cndmask_b32_e32 v14, 0, v21, vcc
	s_waitcnt vmcnt(29)
	v_cndmask_b32_e32 v15, 0, v24, vcc
	s_waitcnt vmcnt(28)
	v_cndmask_b32_e32 v16, 0, v25, vcc
	s_waitcnt vmcnt(27)
	v_cndmask_b32_e32 v17, 0, v26, vcc
	s_waitcnt vmcnt(26)
	v_cndmask_b32_e32 v18, 0, v27, vcc
	s_waitcnt vmcnt(25)
	v_cndmask_b32_e32 v19, 0, v36, vcc
	s_waitcnt vmcnt(24)
	v_cndmask_b32_e32 v20, 0, v37, vcc
	s_waitcnt vmcnt(23)
	v_cndmask_b32_e32 v21, 0, v38, vcc
	s_waitcnt vmcnt(22)
	v_cndmask_b32_e32 v22, 0, v39, vcc
	s_waitcnt vmcnt(21)
	v_cndmask_b32_e32 v23, 0, v40, vcc
	s_waitcnt vmcnt(20)
	v_cndmask_b32_e32 v24, 0, v41, vcc
	s_waitcnt vmcnt(19)
	v_cndmask_b32_e32 v25, 0, v42, vcc
	s_waitcnt vmcnt(18)
	v_cndmask_b32_e32 v26, 0, v43, vcc
	s_waitcnt vmcnt(17)
	v_cndmask_b32_e32 v27, 0, v44, vcc
	s_waitcnt vmcnt(16)
	v_cndmask_b32_e32 v36, 0, v45, vcc
	s_waitcnt vmcnt(15)
	v_cndmask_b32_e32 v37, 0, v46, vcc
	s_waitcnt vmcnt(14)
	v_cndmask_b32_e32 v38, 0, v47, vcc
	s_waitcnt vmcnt(13)
	v_cndmask_b32_e32 v39, 0, v48, vcc
	s_waitcnt vmcnt(12)
	v_cndmask_b32_e32 v40, 0, v49, vcc
	s_waitcnt vmcnt(11)
	v_cndmask_b32_e32 v41, 0, v50, vcc
	s_waitcnt vmcnt(10)
	v_cndmask_b32_e32 v42, 0, v51, vcc
	s_waitcnt vmcnt(9)
	v_cndmask_b32_e32 v43, 0, v52, vcc
	s_waitcnt vmcnt(8)
	v_cndmask_b32_e32 v44, 0, v53, vcc
	s_waitcnt vmcnt(7)
	v_cndmask_b32_e32 v45, 0, v54, vcc
	s_waitcnt vmcnt(6)
	v_cndmask_b32_e32 v46, 0, v55, vcc
	s_waitcnt vmcnt(5)
	v_cndmask_b32_e32 v47, 0, v56, vcc
	s_waitcnt vmcnt(4)
	v_cndmask_b32_e32 v48, 0, v57, vcc
	s_waitcnt vmcnt(3)
	v_cndmask_b32_e32 v49, 0, v58, vcc
	s_waitcnt vmcnt(2)
	v_cndmask_b32_e32 v50, 0, v59, vcc
	s_waitcnt vmcnt(1)
	v_cndmask_b32_e32 v51, 0, v60, vcc
	s_waitcnt vmcnt(0)
	v_cndmask_b32_e32 v12, 0, v12, vcc
	ds_write2_b32 v4, v13, v14 offset1:66
	ds_write2_b32 v4, v15, v16 offset0:132 offset1:198
	ds_write2_b32 v5, v17, v18 offset0:8 offset1:74
	ds_write2_b32 v5, v19, v20 offset0:140 offset1:206
	ds_write2_b32 v6, v21, v22 offset0:16 offset1:82
	ds_write2_b32 v6, v23, v24 offset0:148 offset1:214
	ds_write2_b32 v7, v25, v26 offset0:24 offset1:90
	ds_write2_b32 v7, v27, v36 offset0:156 offset1:222
	ds_write2_b32 v8, v37, v38 offset0:32 offset1:98
	ds_write2_b32 v8, v39, v40 offset0:164 offset1:230
	ds_write2_b32 v9, v41, v42 offset0:40 offset1:106
	ds_write2_b32 v9, v43, v44 offset0:172 offset1:238
	ds_write2_b32 v10, v45, v46 offset0:48 offset1:114
	ds_write2_b32 v10, v47, v48 offset0:180 offset1:246
	ds_write2_b32 v11, v49, v50 offset0:56 offset1:122
	ds_write2_b32 v11, v51, v12 offset0:188 offset1:254
	s_waitcnt lgkmcnt(0)
	ds_read2_b32 v[16:17], v1 offset0:33 offset1:41
	ds_read2_b32 v[18:19], v1 offset1:8
	ds_read2_b32 v[20:21], v1 offset0:66 offset1:74
	ds_read2_b32 v[22:23], v1 offset0:99 offset1:107
	ds_read2_b32 v[24:25], v1 offset0:132 offset1:140
	ds_read2_b32 v[26:27], v1 offset0:165 offset1:173
	ds_read2_b32 v[36:37], v1 offset0:198 offset1:206
	ds_read2_b32 v[38:39], v1 offset0:231 offset1:239
	ds_read2_b32 v[40:41], v1 offset0:49 offset1:57
	ds_read2_b32 v[42:43], v1 offset0:16 offset1:24
	ds_read2_b32 v[44:45], v1 offset0:82 offset1:90
	ds_read2_b32 v[46:47], v1 offset0:115 offset1:123
	ds_read2_b32 v[48:49], v1 offset0:148 offset1:156
	ds_read2_b32 v[50:51], v1 offset0:181 offset1:189
	ds_read2_b32 v[52:53], v1 offset0:214 offset1:222
	ds_read2_b32 v[54:55], v1 offset0:247 offset1:255
	s_waitcnt lgkmcnt(14)
	v_cvt_pk_bf16_f32 v12, v18, v16
	s_waitcnt lgkmcnt(12)
	v_cvt_pk_bf16_f32 v13, v20, v22
	s_waitcnt lgkmcnt(10)
	v_cvt_pk_bf16_f32 v14, v24, v26
	s_waitcnt lgkmcnt(8)
	v_cvt_pk_bf16_f32 v15, v36, v38
	v_cvt_pk_bf16_f32 v16, v19, v17
	v_cvt_pk_bf16_f32 v17, v21, v23
	v_cvt_pk_bf16_f32 v18, v25, v27
	v_cvt_pk_bf16_f32 v19, v37, v39
	s_waitcnt lgkmcnt(6)
	v_cvt_pk_bf16_f32 v20, v42, v40
	s_waitcnt lgkmcnt(4)
	v_cvt_pk_bf16_f32 v21, v44, v46
	s_waitcnt lgkmcnt(2)
	v_cvt_pk_bf16_f32 v22, v48, v50
	s_waitcnt lgkmcnt(0)
	v_cvt_pk_bf16_f32 v23, v52, v54
	v_cvt_pk_bf16_f32 v24, v43, v41
	v_cvt_pk_bf16_f32 v25, v45, v47
	v_cvt_pk_bf16_f32 v26, v49, v51
	v_cvt_pk_bf16_f32 v27, v53, v55
	global_store_dwordx4 v[28:29], v[12:15], off
	global_store_dwordx4 v[30:31], v[16:19], off
	global_store_dwordx4 v[32:33], v[20:23], off
	global_store_dwordx4 v[34:35], v[24:27], off
	s_waitcnt lgkmcnt(0)
	s_cbranch_scc1 .LBB0_8

; __device__ __forceinline__ unsigned pk2(float lo, float hi) { f32x2_p v = {lo, hi}; bf16x2_p b = __builtin_convertvector(v, bf16x2_p); return __builtin_bit_cast(unsigned, b); }
; __device__ __forceinline__ void p_cvt_x(const float* __restrict__ xp, const float* __restrict__ xs, bf16* __restrict__ xb, int gw, int NGW, int lane) {
;     for (int m0 = gw; m0 < M; m0 += 2 * NGW) {
;         const int m1 = m0 + NGW; const bool two = m1 < M;
;         const float* s0 = (m0 < MP) ? xp + (size_t)m0 * DM : xs + (size_t)(m0 - MP) * DM;
;         const int m1c = two ? m1 : m0; const float* s1 = (m1c < MP) ? xp + (size_t)m1c * DM : xs + (size_t)(m1c - MP) * DM;
;         f32x4 v[8];
; #pragma unroll
;         for (int j = 0; j < 2; ++j) { v[2 * j] = *(const f32x4*)(s0 + j * 512 + lane * 8); v[2 * j + 1] = *(const f32x4*)(s0 + j * 512 + lane * 8 + 4); v[4 + 2 * j] = *(const f32x4*)(s1 + j * 512 + lane * 8); v[5 + 2 * j] = *(const f32x4*)(s1 + j * 512 + lane * 8 + 4); }
; #pragma unroll
;         for (int j = 0; j < 2; ++j) { v4u w; w.x = pk2(v[2 * j].x, v[2 * j].y); w.y = pk2(v[2 * j].z, v[2 * j].w); w.z = pk2(v[2 * j + 1].x, v[2 * j + 1].y); w.w = pk2(v[2 * j + 1].z, v[2 * j + 1].w);
;             *(v4u*)(xb + (size_t)m0 * DM + j * 512 + lane * 8) = w;
;             if (two) { v4u w1; w1.x = pk2(v[4 + 2 * j].x, v[4 + 2 * j].y); w1.y = pk2(v[4 + 2 * j].z, v[4 + 2 * j].w); w1.z = pk2(v[5 + 2 * j].x, v[5 + 2 * j].y); w1.w = pk2(v[5 + 2 * j].z, v[5 + 2 * j].w);
;                 *(v4u*)(xb + (size_t)m1 * DM + j * 512 + lane * 8) = w1; } }
.LBB0_12:
	s_load_dwordx16 s[16:31], s[0:1], 0x0
	s_add_i32 s2, s6, s79
	s_add_i32 s3, s6, 0xffffc000
	s_ashr_i32 s7, s6, 31
	s_cmpk_lt_i32 s6, 0x4000
	s_cselect_b32 s5, s7, 0
	s_cselect_b32 s4, s6, s3
	s_waitcnt lgkmcnt(0)
	s_cselect_b32 s3, s17, s19
	s_cselect_b32 s12, s16, s18
	s_lshl_b64 s[4:5], s[4:5], 12
	s_add_u32 s14, s12, s4
	s_addc_u32 s15, s3, s5
	s_cmpk_lt_i32 s2, 0x4200
	s_cselect_b64 s[4:5], -1, 0
	s_and_b64 s[12:13], s[4:5], exec
	s_cselect_b32 s3, s2, s6
	s_add_i32 s12, s3, 0xffffc000
	s_ashr_i32 s13, s3, 31
	s_cmpk_lt_i32 s3, 0x4000
	s_cselect_b32 s13, s13, 0
	s_cselect_b32 s12, s3, s12
	s_cselect_b32 s3, s17, s19
	s_cselect_b32 s16, s16, s18
	s_lshl_b64 s[12:13], s[12:13], 12
	s_add_u32 s12, s16, s12
	global_load_dwordx4 v[26:29], v18, s[14:15] offset:16 nt
	global_load_dwordx4 v[30:33], v18, s[14:15] nt
	s_addc_u32 s13, s3, s13
	global_load_dwordx4 v[10:13], v18, s[14:15] offset:2064 nt
	global_load_dwordx4 v[14:17], v18, s[14:15] offset:2048 nt
	global_load_dwordx4 v[2:5], v18, s[12:13] offset:2064 nt
	global_load_dwordx4 v[6:9], v18, s[12:13] offset:2048 nt
	s_ashr_i32 s3, s2, 31
	s_lshl_b64 s[6:7], s[6:7], 11
	s_lshl_b64 s[14:15], s[2:3], 11
	s_cmpk_gt_i32 s2, 0x41ff
	v_lshl_add_u64 v[24:25], v[20:21], 0, s[6:7]
	v_lshl_add_u64 v[22:23], v[20:21], 0, s[14:15]
	s_waitcnt vmcnt(4)
	v_cvt_pk_bf16_f32 v30, v30, v31
	v_cvt_pk_bf16_f32 v31, v32, v33
	v_cvt_pk_bf16_f32 v32, v26, v27
	v_cvt_pk_bf16_f32 v33, v28, v29
	global_store_dwordx4 v[24:25], v[30:33], off
	s_cbranch_scc1 .LBB0_14
	s_nop 0
	v_lshl_add_u64 v[30:31], s[12:13], 0, v[18:19]
	global_load_dwordx4 v[26:29], v[30:31], off nt
	s_nop 0
	global_load_dwordx4 v[30:33], v[30:31], off offset:16 nt
	s_waitcnt vmcnt(1)
	v_cvt_pk_bf16_f32 v26, v26, v27
	v_cvt_pk_bf16_f32 v27, v28, v29
	s_waitcnt vmcnt(0)
	v_cvt_pk_bf16_f32 v28, v30, v31
	v_cvt_pk_bf16_f32 v29, v32, v33
	global_store_dwordx4 v[22:23], v[26:29], off

; __global__ void __launch_bounds__(NWAVES * 64, 2) mega_fwd(Args args) {
;     ...
;             for (int i = gw * 64 + lane; i < NH * attn_body::BT_N; i += NGW * 64) { const int hh = i / attn_body::BT_N, dl = i % attn_body::BT_N - attn_body::BT_OFF; float v = -INFINITY;
;                 if (dl >= 0) { const int cmul = (dl <= 128 ? 1 : 0) + (((dl & 3) == 0 && dl <= 512) ? 1 : 0) + (((dl & 15) == 0 && dl <= 2048) ? 1 : 0);
;                     if (cmul > 0) v = (in[6][t5_bucket(dl) * NH + hh] + (cmul == 1 ? 0.f : (cmul == 2 ? 0.6931471805599453f : 1.0986122886681098f))) * 1.4426950408889634f; }
;                 btg[i] = v; } }
.LBB0_18:
	s_or_b64 exec, exec, s[6:7]
	s_load_dwordx16 s[56:71], s[0:1], 0x0
	v_lshl_add_u32 v8, v7, 3, v5
	v_ashrrev_i32_e32 v9, 31, v8
	v_cmp_eq_u32_e32 vcc, 2, v6
	s_waitcnt lgkmcnt(0)
	v_lshl_add_u64 v[8:9], v[8:9], 2, s[68:69]
	global_load_dword v5, v[8:9], off nt
	v_cndmask_b32_e32 v7, v1, v3, vcc
	v_cmp_ne_u32_e32 vcc, 1, v6
	s_nop 1
	v_cndmask_b32_e32 v6, 0, v7, vcc
	s_waitcnt vmcnt(0)
	v_add_f32_e32 v5, v6, v5
	v_mul_f32_e32 v7, 0x3fb8aa3b, v5

; __global__ void __launch_bounds__(NWAVES * 64, 2) mega_fwd(Args args) {
;     ...
;             for (int i = gw * 64 + lane; i < NH * 392; i += NGW * 64) { const int hh = i / 392, e = i % 392; float v = -INFINITY;
;                 if (e < 387) { const int pat = e / 129, dl = (e % 129) << (2 * pat); v = in[6][t5_bucket(dl) * NH + hh]; }
;                 sb[i] = v; } }
.LBB0_27:
	s_or_b64 exec, exec, s[6:7]
	v_lshl_add_u32 v4, v4, 3, v3
	v_readlane_b32 s56, v245, 5
	v_ashrrev_i32_e32 v5, 31, v4
	v_readlane_b32 s68, v245, 17
	v_readlane_b32 s69, v245, 18
	v_readlane_b32 s57, v245, 6
	v_readlane_b32 s58, v245, 7
	v_lshl_add_u64 v[4:5], v[4:5], 2, s[68:69]
	global_load_dword v4, v[4:5], off nt
	v_readlane_b32 s59, v245, 8
	v_readlane_b32 s60, v245, 9
	v_readlane_b32 s61, v245, 10
	v_readlane_b32 s62, v245, 11
	v_readlane_b32 s63, v245, 12
	v_readlane_b32 s64, v245, 13
	v_readlane_b32 s65, v245, 14
	v_readlane_b32 s66, v245, 15
	v_readlane_b32 s67, v245, 16
	v_readlane_b32 s70, v245, 19
	v_readlane_b32 s71, v245, 20

;     __device__ __forceinline__ void fused(f32x4 (&acc)[2][2][4][2], const Unit& u, int wr, int wc, int fr, int fq, PG8_LAS unsigned char* lds, int wid, int lane) const {
;     ...
;             for (int m = 0; m < 4; ++m) { const size_t off = (size_t)(u.pm * BM + ai * HALF + wr * 64 + m * 16 + fr) * ldc + col0;
; #pragma unroll
;                 for (int bj = 0; bj < 2; ++bj) { f32x4 b0, b1;
;                     if (base) { b0 = *(const f32x4*)(base + off + bj * HALF); b1 = *(const f32x4*)(base + off + bj * HALF + 4); }
;                     else { const u32x4 w = *(const u32x4*)(baseb + off + bj * HALF);
;                         b0 = (f32x4){__uint_as_float(w.x << 16), __uint_as_float(w.x & 0xffff0000u), __uint_as_float(w.y << 16), __uint_as_float(w.y & 0xffff0000u)};
;                         b1 = (f32x4){__uint_as_float(w.z << 16), __uint_as_float(w.z & 0xffff0000u), __uint_as_float(w.w << 16), __uint_as_float(w.w & 0xffff0000u)}; }
;                     acc[ai][bj][m][0] = acc[ai][bj][m][0] * s + b0 * alpha; acc[ai][bj][m][1] = acc[ai][bj][m][1] * s + b1 * alpha; }
.LBB0_194:
	s_lshl_b32 s0, s27, 5
	s_lshl_b32 s1, s60, 8
	v_lshrrev_b32_e32 v132, 1, v2
	s_or_b32 s0, s1, s0
	s_lshl_b32 s16, s25, 8
	v_and_or_b32 v164, v132, 24, s0
	s_add_i32 s0, s16, s36
	v_or_b32_e32 v134, s0, v152
	v_readlane_b32 s0, v245, 5
	v_readlane_b32 s4, v245, 9
	v_readlane_b32 s5, v245, 10
	v_readlane_b32 s6, v245, 11
	v_readlane_b32 s7, v245, 12
	v_readlane_b32 s8, v245, 13
	v_readlane_b32 s9, v245, 14
	v_readlane_b32 s10, v245, 15
	v_readlane_b32 s11, v245, 16
	v_readlane_b32 s12, v245, 17
	v_readlane_b32 s13, v245, 18
	v_readlane_b32 s14, v245, 19
	v_readlane_b32 s15, v245, 20
	v_ashrrev_i32_e32 v135, 31, v134
	v_readlane_b32 s1, v245, 6
	v_readlane_b32 s2, v245, 7
	v_readlane_b32 s3, v245, 8
	s_mov_b64 s[14:15], s[10:11]
	v_ashrrev_i32_e32 v165, 31, v164
	v_lshlrev_b64 v[132:133], 12, v[134:135]
	s_mov_b64 s[12:13], s[8:9]
	s_mov_b64 s[10:11], s[6:7]
	s_mov_b64 s[8:9], s[4:5]
	s_mov_b64 s[6:7], s[2:3]
	s_mov_b64 s[4:5], s[0:1]
	v_lshl_add_u64 v[136:137], s[4:5], 0, v[132:133]
	v_lshlrev_b64 v[132:133], 2, v[164:165]
	v_lshl_add_u64 v[148:149], v[136:137], 0, v[132:133]
	s_barrier
	s_nop 1
	v_subrev_u32_e32 v242, s4, v148
	global_load_dwordx4 v[176:179], v242, s[4:5] nt
	global_load_dwordx4 v[180:183], v242, s[4:5] offset:16 nt
	global_load_dwordx4 v[184:187], v242, s[4:5] offset:512 nt
	global_load_dwordx4 v[188:191], v242, s[4:5] offset:528 nt
	s_add_u32 s100, s4, 0x10000
	s_addc_u32 s101, s5, 0
	global_load_dwordx4 v[192:195], v242, s[100:101] nt
	global_load_dwordx4 v[198:201], v242, s[100:101] offset:16 nt
	global_load_dwordx4 v[202:205], v242, s[100:101] offset:512 nt
	global_load_dwordx4 v[206:209], v242, s[100:101] offset:528 nt
	s_add_u32 s98, s4, 0x20000
	s_addc_u32 s99, s5, 0
	global_load_dwordx4 v[210:213], v242, s[98:99] nt
	global_load_dwordx4 v[214:217], v242, s[98:99] offset:16 nt
	global_load_dwordx4 v[218:221], v242, s[98:99] offset:512 nt
	global_load_dwordx4 v[222:225], v242, s[98:99] offset:528 nt
	s_add_u32 s100, s4, 0x30000
	s_addc_u32 s101, s5, 0
	global_load_dwordx4 v[226:229], v242, s[100:101] nt
	global_load_dwordx4 v[230:233], v242, s[100:101] offset:16 nt
	global_load_dwordx4 v[246:249], v242, s[100:101] offset:512 nt
	global_load_dwordx4 v[250:253], v242, s[100:101] offset:528 nt
	s_nop 0
	v_or_b32_e32 v154, 16, v134
	v_ashrrev_i32_e32 v155, 31, v154
	s_mov_b32 s0, 0x3f9837f0
	v_lshlrev_b64 v[154:155], 12, v[154:155]
	v_lshl_add_u64 v[154:155], s[4:5], 0, v[154:155]
	v_lshl_add_u64 v[154:155], v[154:155], 0, v[132:133]
	v_mbcnt_lo_u32_b32 v135, -1, 0
	v_mbcnt_hi_u32_b32 v153, -1, v135
	v_and_b32_e32 v135, 64, v153
	v_add_u32_e32 v174, 64, v135
	s_waitcnt vmcnt(12)
	v_pk_mul_f32 v[138:139], v[178:179], s[0:1] op_sel_hi:[1,0]
	v_pk_mul_f32 v[136:137], v[176:177], s[0:1] op_sel_hi:[1,0]
	v_pk_mul_f32 v[142:143], v[182:183], s[0:1] op_sel_hi:[1,0]
	v_pk_mul_f32 v[140:141], v[180:181], s[0:1] op_sel_hi:[1,0]
	v_pk_mul_f32 v[146:147], v[186:187], s[0:1] op_sel_hi:[1,0]
	v_pk_mul_f32 v[144:145], v[184:185], s[0:1] op_sel_hi:[1,0]
	v_pk_mul_f32 v[150:151], v[190:191], s[0:1] op_sel_hi:[1,0]
	v_pk_mul_f32 v[148:149], v[188:189], s[0:1] op_sel_hi:[1,0]
	v_pk_fma_f32 v[114:115], v[114:115], 0.5, v[138:139] op_sel_hi:[1,0,1]
	v_pk_fma_f32 v[112:113], v[112:113], 0.5, v[136:137] op_sel_hi:[1,0,1]
	v_pk_fma_f32 v[126:127], v[126:127], 0.5, v[142:143] op_sel_hi:[1,0,1]
	v_pk_fma_f32 v[124:125], v[124:125], 0.5, v[140:141] op_sel_hi:[1,0,1]
	v_pk_fma_f32 v[110:111], v[110:111], 0.5, v[146:147] op_sel_hi:[1,0,1]
	v_pk_fma_f32 v[108:109], v[108:109], 0.5, v[144:145] op_sel_hi:[1,0,1]
	v_pk_fma_f32 v[94:95], v[94:95], 0.5, v[150:151] op_sel_hi:[1,0,1]
	v_pk_fma_f32 v[92:93], v[92:93], 0.5, v[148:149] op_sel_hi:[1,0,1]
	s_nop 0
	s_add_u32 s98, s4, 0x80000
	s_addc_u32 s99, s5, 0
	global_load_dwordx4 v[176:179], v242, s[98:99] nt
	global_load_dwordx4 v[180:183], v242, s[98:99] offset:16 nt
	global_load_dwordx4 v[184:187], v242, s[98:99] offset:512 nt
	global_load_dwordx4 v[188:191], v242, s[98:99] offset:528 nt
	v_or_b32_e32 v154, 32, v134
	v_ashrrev_i32_e32 v155, 31, v154
	v_lshlrev_b64 v[154:155], 12, v[154:155]
	v_lshl_add_u64 v[154:155], s[4:5], 0, v[154:155]
	v_lshl_add_u64 v[154:155], v[154:155], 0, v[132:133]
	v_mov_b32_e32 v158, v113
	v_mov_b32_e32 v159, v114
	v_mov_b32_e32 v160, v112
	v_mov_b32_e32 v161, v115
	v_pk_add_f32 v[158:159], v[158:159], v[160:161]
	v_add_f32_e32 v163, v108, v109
	v_add_f32_e32 v167, v110, v111
	v_mov_b32_e32 v162, v92
	v_mov_b32_e32 v166, v93
	v_mov_b32_e32 v172, v95
	s_waitcnt vmcnt(15)
	v_pk_mul_f32 v[138:139], v[194:195], s[0:1] op_sel_hi:[1,0]
	v_pk_mul_f32 v[136:137], v[192:193], s[0:1] op_sel_hi:[1,0]
	s_waitcnt vmcnt(14)
	v_pk_mul_f32 v[142:143], v[200:201], s[0:1] op_sel_hi:[1,0]
	v_pk_mul_f32 v[140:141], v[198:199], s[0:1] op_sel_hi:[1,0]
	s_waitcnt vmcnt(13)
	v_pk_mul_f32 v[146:147], v[204:205], s[0:1] op_sel_hi:[1,0]
	v_pk_mul_f32 v[144:145], v[202:203], s[0:1] op_sel_hi:[1,0]
	s_waitcnt vmcnt(12)
	v_pk_mul_f32 v[150:151], v[208:209], s[0:1] op_sel_hi:[1,0]
	v_pk_mul_f32 v[148:149], v[206:207], s[0:1] op_sel_hi:[1,0]
	v_pk_fma_f32 v[98:99], v[98:99], 0.5, v[138:139] op_sel_hi:[1,0,1]
	v_pk_fma_f32 v[96:97], v[96:97], 0.5, v[136:137] op_sel_hi:[1,0,1]
	v_pk_fma_f32 v[130:131], v[130:131], 0.5, v[142:143] op_sel_hi:[1,0,1]
	v_pk_fma_f32 v[128:129], v[128:129], 0.5, v[140:141] op_sel_hi:[1,0,1]
	v_pk_fma_f32 v[82:83], v[82:83], 0.5, v[146:147] op_sel_hi:[1,0,1]
	v_pk_fma_f32 v[80:81], v[80:81], 0.5, v[144:145] op_sel_hi:[1,0,1]
	v_pk_fma_f32 v[70:71], v[70:71], 0.5, v[150:151] op_sel_hi:[1,0,1]
	v_pk_fma_f32 v[68:69], v[68:69], 0.5, v[148:149] op_sel_hi:[1,0,1]
	s_nop 0
	s_add_u32 s100, s4, 0x90000
	s_addc_u32 s101, s5, 0
	global_load_dwordx4 v[192:195], v242, s[100:101] nt
	global_load_dwordx4 v[198:201], v242, s[100:101] offset:16 nt
	global_load_dwordx4 v[202:205], v242, s[100:101] offset:512 nt
	global_load_dwordx4 v[206:209], v242, s[100:101] offset:528 nt
	v_or_b32_e32 v154, 48, v134
	v_ashrrev_i32_e32 v155, 31, v154
	v_lshlrev_b64 v[154:155], 12, v[154:155]
	v_lshl_add_u64 v[154:155], s[4:5], 0, v[154:155]
	v_lshl_add_u64 v[154:155], v[154:155], 0, v[132:133]
	s_waitcnt vmcnt(15)
;     __device__ __forceinline__ void fused(f32x4 (&acc)[2][2][4][2], const Unit& u, int wr, int wc, int fr, int fq, PG8_LAS unsigned char* lds, int wid, int lane) const {
;     ...
;             for (int m = 0; m < 4; ++m) { const size_t off = (size_t)(u.pm * BM + ai * HALF + wr * 64 + m * 16 + fr) * ldc + col0;
; #pragma unroll
;                 for (int bj = 0; bj < 2; ++bj) { f32x4 b0, b1;
;                     if (base) { b0 = *(const f32x4*)(base + off + bj * HALF); b1 = *(const f32x4*)(base + off + bj * HALF + 4); }
;                     else { const u32x4 w = *(const u32x4*)(baseb + off + bj * HALF);
;                         b0 = (f32x4){__uint_as_float(w.x << 16), __uint_as_float(w.x & 0xffff0000u), __uint_as_float(w.y << 16), __uint_as_float(w.y & 0xffff0000u)};
;                         b1 = (f32x4){__uint_as_float(w.z << 16), __uint_as_float(w.z & 0xffff0000u), __uint_as_float(w.w << 16), __uint_as_float(w.w & 0xffff0000u)}; }
;                     acc[ai][bj][m][0] = acc[ai][bj][m][0] * s + b0 * alpha; acc[ai][bj][m][1] = acc[ai][bj][m][1] * s + b1 * alpha; }
	v_pk_mul_f32 v[138:139], v[212:213], s[0:1] op_sel_hi:[1,0]
	v_pk_mul_f32 v[136:137], v[210:211], s[0:1] op_sel_hi:[1,0]
	s_waitcnt vmcnt(14)
	v_pk_mul_f32 v[142:143], v[216:217], s[0:1] op_sel_hi:[1,0]
	v_pk_mul_f32 v[140:141], v[214:215], s[0:1] op_sel_hi:[1,0]
	s_waitcnt vmcnt(13)
	v_pk_mul_f32 v[146:147], v[220:221], s[0:1] op_sel_hi:[1,0]
	v_pk_mul_f32 v[144:145], v[218:219], s[0:1] op_sel_hi:[1,0]
	s_waitcnt vmcnt(12)
	v_pk_mul_f32 v[150:151], v[224:225], s[0:1] op_sel_hi:[1,0]
	v_pk_mul_f32 v[148:149], v[222:223], s[0:1] op_sel_hi:[1,0]
	v_pk_fma_f32 v[102:103], v[102:103], 0.5, v[138:139] op_sel_hi:[1,0,1]
	v_pk_fma_f32 v[100:101], v[100:101], 0.5, v[136:137] op_sel_hi:[1,0,1]
	v_pk_fma_f32 v[118:119], v[118:119], 0.5, v[142:143] op_sel_hi:[1,0,1]
	v_pk_fma_f32 v[116:117], v[116:117], 0.5, v[140:141] op_sel_hi:[1,0,1]
	v_pk_fma_f32 v[86:87], v[86:87], 0.5, v[146:147] op_sel_hi:[1,0,1]
	v_pk_fma_f32 v[84:85], v[84:85], 0.5, v[144:145] op_sel_hi:[1,0,1]
	v_pk_fma_f32 v[74:75], v[74:75], 0.5, v[150:151] op_sel_hi:[1,0,1]
	v_pk_fma_f32 v[72:73], v[72:73], 0.5, v[148:149] op_sel_hi:[1,0,1]
	s_nop 0
	s_add_u32 s98, s4, 0xa0000
	s_addc_u32 s99, s5, 0
	global_load_dwordx4 v[210:213], v242, s[98:99] nt
	global_load_dwordx4 v[214:217], v242, s[98:99] offset:16 nt
	global_load_dwordx4 v[218:221], v242, s[98:99] offset:512 nt
	global_load_dwordx4 v[222:225], v242, s[98:99] offset:528 nt
	v_add_u32_e32 v154, 0x80, v134
	v_ashrrev_i32_e32 v155, 31, v154
	v_lshlrev_b64 v[154:155], 12, v[154:155]
	v_lshl_add_u64 v[154:155], s[4:5], 0, v[154:155]
	v_lshl_add_u64 v[154:155], v[154:155], 0, v[132:133]
	s_waitcnt vmcnt(15)
	v_pk_mul_f32 v[138:139], v[228:229], s[0:1] op_sel_hi:[1,0]
	v_pk_mul_f32 v[136:137], v[226:227], s[0:1] op_sel_hi:[1,0]
	s_waitcnt vmcnt(14)
	v_pk_mul_f32 v[142:143], v[232:233], s[0:1] op_sel_hi:[1,0]
	v_pk_mul_f32 v[140:141], v[230:231], s[0:1] op_sel_hi:[1,0]
	s_waitcnt vmcnt(13)
	v_pk_mul_f32 v[146:147], v[248:249], s[0:1] op_sel_hi:[1,0]
	v_pk_mul_f32 v[144:145], v[246:247], s[0:1] op_sel_hi:[1,0]
	s_waitcnt vmcnt(12)
	v_pk_mul_f32 v[150:151], v[252:253], s[0:1] op_sel_hi:[1,0]
	v_pk_mul_f32 v[148:149], v[250:251], s[0:1] op_sel_hi:[1,0]
	v_pk_fma_f32 v[106:107], v[106:107], 0.5, v[138:139] op_sel_hi:[1,0,1]
	v_pk_fma_f32 v[104:105], v[104:105], 0.5, v[136:137] op_sel_hi:[1,0,1]
	v_pk_fma_f32 v[122:123], v[122:123], 0.5, v[142:143] op_sel_hi:[1,0,1]
	v_pk_fma_f32 v[120:121], v[120:121], 0.5, v[140:141] op_sel_hi:[1,0,1]
	v_pk_fma_f32 v[90:91], v[90:91], 0.5, v[146:147] op_sel_hi:[1,0,1]
	v_pk_fma_f32 v[88:89], v[88:89], 0.5, v[144:145] op_sel_hi:[1,0,1]
	v_pk_fma_f32 v[78:79], v[78:79], 0.5, v[150:151] op_sel_hi:[1,0,1]
	v_pk_fma_f32 v[76:77], v[76:77], 0.5, v[148:149] op_sel_hi:[1,0,1]
	s_nop 0
	s_add_u32 s100, s4, 0xb0000
	s_addc_u32 s101, s5, 0
	global_load_dwordx4 v[226:229], v242, s[100:101] offset:16 nt
	global_load_dwordx4 v[230:233], v242, s[100:101] nt
	global_load_dwordx4 v[246:249], v242, s[100:101] offset:528 nt
	global_load_dwordx4 v[250:253], v242, s[100:101] offset:512 nt
	v_add_u32_e32 v154, 0x90, v134
	v_ashrrev_i32_e32 v155, 31, v154
	v_lshlrev_b64 v[154:155], 12, v[154:155]
	v_lshl_add_u64 v[154:155], s[4:5], 0, v[154:155]
	v_lshl_add_u64 v[154:155], v[154:155], 0, v[132:133]
	s_waitcnt vmcnt(15)
	v_pk_mul_f32 v[138:139], v[178:179], s[0:1] op_sel_hi:[1,0]
	v_pk_mul_f32 v[136:137], v[176:177], s[0:1] op_sel_hi:[1,0]
	s_waitcnt vmcnt(14)
	v_pk_mul_f32 v[142:143], v[182:183], s[0:1] op_sel_hi:[1,0]
	v_pk_mul_f32 v[140:141], v[180:181], s[0:1] op_sel_hi:[1,0]
	s_waitcnt vmcnt(13)
	v_pk_mul_f32 v[146:147], v[186:187], s[0:1] op_sel_hi:[1,0]
	v_pk_mul_f32 v[144:145], v[184:185], s[0:1] op_sel_hi:[1,0]
	s_waitcnt vmcnt(12)
	v_pk_mul_f32 v[150:151], v[190:191], s[0:1] op_sel_hi:[1,0]
	v_pk_mul_f32 v[148:149], v[188:189], s[0:1] op_sel_hi:[1,0]
	v_pk_fma_f32 v[66:67], v[66:67], 0.5, v[138:139] op_sel_hi:[1,0,1]
	v_pk_fma_f32 v[64:65], v[64:65], 0.5, v[136:137] op_sel_hi:[1,0,1]
	v_pk_fma_f32 v[62:63], v[62:63], 0.5, v[142:143] op_sel_hi:[1,0,1]
	v_pk_fma_f32 v[60:61], v[60:61], 0.5, v[140:141] op_sel_hi:[1,0,1]
	v_pk_fma_f32 v[58:59], v[58:59], 0.5, v[146:147] op_sel_hi:[1,0,1]
	v_pk_fma_f32 v[56:57], v[56:57], 0.5, v[144:145] op_sel_hi:[1,0,1]
	v_pk_fma_f32 v[54:55], v[54:55], 0.5, v[150:151] op_sel_hi:[1,0,1]
	v_pk_fma_f32 v[52:53], v[52:53], 0.5, v[148:149] op_sel_hi:[1,0,1]
	s_nop 0
	v_add_u32_e32 v154, 0xa0, v134
	v_ashrrev_i32_e32 v155, 31, v154
	v_lshlrev_b64 v[154:155], 12, v[154:155]
	v_lshl_add_u64 v[154:155], s[4:5], 0, v[154:155]
	v_lshl_add_u64 v[154:155], v[154:155], 0, v[132:133]
	v_add_u32_e32 v134, 0xb0, v134
	v_ashrrev_i32_e32 v135, 31, v134
	s_waitcnt vmcnt(11)
	v_pk_mul_f32 v[138:139], v[194:195], s[0:1] op_sel_hi:[1,0]
	v_pk_mul_f32 v[136:137], v[192:193], s[0:1] op_sel_hi:[1,0]
	s_waitcnt vmcnt(10)
	v_pk_mul_f32 v[142:143], v[200:201], s[0:1] op_sel_hi:[1,0]
	v_pk_mul_f32 v[140:141], v[198:199], s[0:1] op_sel_hi:[1,0]
	s_waitcnt vmcnt(9)
	v_pk_mul_f32 v[146:147], v[204:205], s[0:1] op_sel_hi:[1,0]
	v_pk_mul_f32 v[144:145], v[202:203], s[0:1] op_sel_hi:[1,0]
	s_waitcnt vmcnt(8)
	v_pk_mul_f32 v[150:151], v[208:209], s[0:1] op_sel_hi:[1,0]
	v_pk_mul_f32 v[148:149], v[206:207], s[0:1] op_sel_hi:[1,0]
	v_pk_fma_f32 v[50:51], v[50:51], 0.5, v[138:139] op_sel_hi:[1,0,1]
	v_pk_fma_f32 v[48:49], v[48:49], 0.5, v[136:137] op_sel_hi:[1,0,1]
	v_pk_fma_f32 v[46:47], v[46:47], 0.5, v[142:143] op_sel_hi:[1,0,1]
	v_pk_fma_f32 v[44:45], v[44:45], 0.5, v[140:141] op_sel_hi:[1,0,1]
	v_pk_fma_f32 v[42:43], v[42:43], 0.5, v[146:147] op_sel_hi:[1,0,1]
	v_pk_fma_f32 v[40:41], v[40:41], 0.5, v[144:145] op_sel_hi:[1,0,1]
	v_pk_fma_f32 v[38:39], v[38:39], 0.5, v[150:151] op_sel_hi:[1,0,1]
	v_pk_fma_f32 v[36:37], v[36:37], 0.5, v[148:149] op_sel_hi:[1,0,1]
	s_nop 0
	v_xor_b32_e32 v154, 16, v153
	v_cmp_lt_i32_e32 vcc, v154, v174
	s_waitcnt vmcnt(7)
;     __device__ __forceinline__ bool run(const f32x4 (&v)[2][2][4][2], const Unit& u, int wr, int wc, int fr, int fq, PG8_LAS unsigned char* lds, int wid, int lane) const {
;     ...
;                     for (int n = 0; n < 2; ++n) { const f32x4 x = v[ai][bj][m][n]; s += (x[0] + x[1]) + (x[2] + x[3]); }
;                 s += __shfl_xor(s, 16); s += __shfl_xor(s, 32);
;                 const float mw = s * (1.0f / 64.0f); float q = 0.f;
; #pragma unroll
;                 for (int bj = 0; bj < 2; ++bj)
; #pragma unroll
;                     for (int n = 0; n < 2; ++n) { const f32x4 d = v[ai][bj][m][n] - mw; q += (d[0] * d[0] + d[1] * d[1]) + (d[2] * d[2] + d[3] * d[3]); }
;                 q += __shfl_xor(q, 16); q += __shfl_xor(q, 32);
;                 if (fq == 0) P[(ai * HALF + wr * 64 + m * 16 + fr) * 4 + wc] = (f32x2v){mw, q};
	v_pk_mul_f32 v[138:139], v[212:213], s[0:1] op_sel_hi:[1,0]
	v_cndmask_b32_e32 v156, v153, v154, vcc
	v_lshlrev_b64 v[154:155], 12, v[134:135]
	v_lshl_add_u64 v[154:155], s[4:5], 0, v[154:155]
	v_pk_mul_f32 v[136:137], v[210:211], s[0:1] op_sel_hi:[1,0]
	s_waitcnt vmcnt(6)
	v_pk_mul_f32 v[142:143], v[216:217], s[0:1] op_sel_hi:[1,0]
	v_pk_mul_f32 v[140:141], v[214:215], s[0:1] op_sel_hi:[1,0]
	s_waitcnt vmcnt(5)
	v_pk_mul_f32 v[146:147], v[220:221], s[0:1] op_sel_hi:[1,0]
	v_pk_mul_f32 v[144:145], v[218:219], s[0:1] op_sel_hi:[1,0]
	s_waitcnt vmcnt(4)
	v_pk_mul_f32 v[150:151], v[224:225], s[0:1] op_sel_hi:[1,0]
	v_pk_mul_f32 v[148:149], v[222:223], s[0:1] op_sel_hi:[1,0]
	v_lshl_add_u64 v[154:155], v[154:155], 0, v[132:133]
	v_pk_fma_f32 v[34:35], v[34:35], 0.5, v[138:139] op_sel_hi:[1,0,1]
	v_pk_fma_f32 v[32:33], v[32:33], 0.5, v[136:137] op_sel_hi:[1,0,1]
	v_pk_fma_f32 v[30:31], v[30:31], 0.5, v[142:143] op_sel_hi:[1,0,1]
	v_pk_fma_f32 v[28:29], v[28:29], 0.5, v[140:141] op_sel_hi:[1,0,1]
	v_pk_fma_f32 v[26:27], v[26:27], 0.5, v[146:147] op_sel_hi:[1,0,1]
	v_pk_fma_f32 v[24:25], v[24:25], 0.5, v[144:145] op_sel_hi:[1,0,1]
	v_pk_fma_f32 v[22:23], v[22:23], 0.5, v[150:151] op_sel_hi:[1,0,1]
	v_pk_fma_f32 v[20:21], v[20:21], 0.5, v[148:149] op_sel_hi:[1,0,1]
	v_lshlrev_b32_e32 v134, 2, v156
	s_nop 0
	v_mov_b32_e32 v136, v125
	v_mov_b32_e32 v137, v126
	v_mov_b32_e32 v138, v124
	v_mov_b32_e32 v139, v127
	v_pk_add_f32 v[136:137], v[136:137], v[138:139]
	v_add_f32_e32 v135, v158, v159
	v_pk_add_f32 v[136:137], v[136:137], v[136:137] op_sel_hi:[0,1]
	v_add_f32_e32 v173, 0, v135
	v_mov_b32_e32 v136, v94
	v_pk_add_f32 v[138:139], v[162:163], v[166:167]
	v_pk_add_f32 v[136:137], v[136:137], v[172:173]
	v_xor_b32_e32 v135, 32, v153
	v_pk_add_f32 v[136:137], v[138:139], v[136:137]
	v_cmp_lt_i32_e32 vcc, v135, v174
	v_add_f32_e32 v136, v136, v137
	v_mov_b32_e32 v137, v136
	s_nop 1
	v_permlane16_swap_b32 v136, v137
	v_cndmask_b32_e32 v135, v153, v135, vcc
	v_lshlrev_b32_e32 v135, 2, v135
	s_waitcnt lgkmcnt(0)
	v_add_f32_e32 v136, v136, v137
	v_mov_b32_e32 v137, v136
	s_nop 1
	v_permlane32_swap_b32 v136, v137
	s_waitcnt lgkmcnt(0)
	v_add_f32_e32 v137, v136, v137
	v_fmamk_f32 v138, v137, 0xbc800000, v115
	v_fmamk_f32 v153, v137, 0xbc800000, v113
	v_fmamk_f32 v159, v137, 0xbc800000, v127
	v_fmamk_f32 v161, v137, 0xbc800000, v125
	v_fmamk_f32 v136, v137, 0xbc800000, v114
	v_fmamk_f32 v139, v137, 0xbc800000, v112
	v_fmamk_f32 v158, v137, 0xbc800000, v126
	v_fmamk_f32 v160, v137, 0xbc800000, v124
	v_fmamk_f32 v163, v137, 0xbc800000, v111
	v_fmamk_f32 v167, v137, 0xbc800000, v109
	v_mul_f32_e32 v153, v153, v153
	v_mul_f32_e32 v138, v138, v138
	v_mul_f32_e32 v161, v161, v161
	v_mul_f32_e32 v159, v159, v159
	v_fmamk_f32 v162, v137, 0xbc800000, v110
	v_fmamk_f32 v166, v137, 0xbc800000, v108
	v_fmamk_f32 v173, v137, 0xbc800000, v95
	v_fmamk_f32 v175, v137, 0xbc800000, v93
	v_mul_f32_e32 v167, v167, v167
	v_mul_f32_e32 v163, v163, v163
	v_fmac_f32_e32 v153, v139, v139
	v_fmac_f32_e32 v138, v136, v136
	v_fmac_f32_e32 v161, v160, v160
	v_fmac_f32_e32 v159, v158, v158
	v_fmamk_f32 v172, v137, 0xbc800000, v94
	v_fmamk_f32 v174, v137, 0xbc800000, v92
	v_mul_f32_e32 v175, v175, v175
	v_mul_f32_e32 v173, v173, v173
	v_fmac_f32_e32 v167, v166, v166
	v_fmac_f32_e32 v163, v162, v162
	v_add_f32_e32 v136, v153, v138
	v_add_f32_e32 v138, v161, v159
	v_fmac_f32_e32 v175, v174, v174
	v_fmac_f32_e32 v173, v172, v172
	v_add_f32_e32 v139, v167, v163
	v_add_f32_e32 v136, v136, v138
	v_add_f32_e32 v153, v175, v173
	v_add_f32_e32 v136, v139, v136
	v_add_f32_e32 v138, v153, v136
	v_mov_b32_e32 v139, v138
	s_nop 1
	v_permlane16_swap_b32 v138, v139
	v_and_b32_e32 v136, 63, v2
	v_cmp_gt_u32_e32 vcc, 16, v136
	s_waitcnt lgkmcnt(0)
	v_add_f32_e32 v138, v138, v139
	v_mov_b32_e32 v139, v138
	s_nop 1
	v_permlane32_swap_b32 v138, v139
	s_waitcnt vmcnt(3)
	v_pk_mul_f32 v[142:143], v[228:229], s[0:1] op_sel_hi:[1,0]
	s_waitcnt vmcnt(2)
	v_pk_mul_f32 v[146:147], v[232:233], s[0:1] op_sel_hi:[1,0]
	v_pk_mul_f32 v[144:145], v[230:231], s[0:1] op_sel_hi:[1,0]
	v_pk_mul_f32 v[140:141], v[226:227], s[0:1] op_sel_hi:[1,0]
	s_waitcnt vmcnt(0)
	v_pk_mul_f32 v[156:157], v[252:253], s[0:1] op_sel_hi:[1,0]
	v_pk_mul_f32 v[154:155], v[250:251], s[0:1] op_sel_hi:[1,0]
	v_pk_mul_f32 v[150:151], v[248:249], s[0:1] op_sel_hi:[1,0]
	v_pk_mul_f32 v[148:149], v[246:247], s[0:1] op_sel_hi:[1,0]
	v_pk_fma_f32 v[18:19], v[18:19], 0.5, v[146:147] op_sel_hi:[1,0,1]
	v_pk_fma_f32 v[16:17], v[16:17], 0.5, v[144:145] op_sel_hi:[1,0,1]
	v_pk_fma_f32 v[14:15], v[14:15], 0.5, v[142:143] op_sel_hi:[1,0,1]
	v_pk_fma_f32 v[12:13], v[12:13], 0.5, v[140:141] op_sel_hi:[1,0,1]
	v_pk_fma_f32 v[10:11], v[10:11], 0.5, v[156:157] op_sel_hi:[1,0,1]
	v_pk_fma_f32 v[8:9], v[8:9], 0.5, v[154:155] op_sel_hi:[1,0,1]
	v_pk_fma_f32 v[6:7], v[6:7], 0.5, v[150:151] op_sel_hi:[1,0,1]
	v_pk_fma_f32 v[4:5], v[4:5], 0.5, v[148:149] op_sel_hi:[1,0,1]
	s_lshl_b32 s0, s27, 3
	s_add_i32 s2, s0, 0
	s_and_saveexec_b64 s[0:1], vcc
	s_cbranch_execz .LBB0_196
	s_lshl_b32 s3, s26, 11
	s_add_i32 s3, s2, s3
	v_mul_f32_e32 v140, 0x3c800000, v137
	v_lshl_add_u32 v137, v152, 5, s3
	s_waitcnt lgkmcnt(0)
	v_add_f32_e32 v141, v138, v139
	ds_write_b64 v137, v[140:141]

;     __device__ __forceinline__ void fused(f32x4 (&acc)[2][2][4][2], const Unit& u, int wr, int wc, int fr, int fq, PG8_LAS unsigned char* lds, int wid, int lane) const {
;     ...
;             for (int m = 0; m < 4; ++m) { const size_t off = (size_t)(u.pm * BM + ai * HALF + wr * 64 + m * 16 + fr) * ldc + col0;
; #pragma unroll
;                 for (int bj = 0; bj < 2; ++bj) { f32x4 b0, b1;
;                     if (base) { b0 = *(const f32x4*)(base + off + bj * HALF); b1 = *(const f32x4*)(base + off + bj * HALF + 4); }
;                     else { const u32x4 w = *(const u32x4*)(baseb + off + bj * HALF);
;                         b0 = (f32x4){__uint_as_float(w.x << 16), __uint_as_float(w.x & 0xffff0000u), __uint_as_float(w.y << 16), __uint_as_float(w.y & 0xffff0000u)};
;                         b1 = (f32x4){__uint_as_float(w.z << 16), __uint_as_float(w.z & 0xffff0000u), __uint_as_float(w.w << 16), __uint_as_float(w.w & 0xffff0000u)}; }
;                     acc[ai][bj][m][0] = acc[ai][bj][m][0] * s + b0 * alpha; acc[ai][bj][m][1] = acc[ai][bj][m][1] * s + b1 * alpha; }
.LBB0_1496:
	s_lshl_b32 s0, s13, 5
	s_lshl_b32 s1, s20, 8
	v_lshrrev_b32_e32 v130, 1, v150
	s_or_b32 s0, s1, s0
	s_lshl_b32 s22, s12, 8
	v_and_or_b32 v130, v130, 24, s0
	s_add_i32 s0, s22, s35
	v_or_b32_e32 v132, s0, v151
	v_ashrrev_i32_e32 v133, 31, v132
	v_readlane_b32 s2, v245, 57
	v_ashrrev_i32_e32 v131, 31, v130
	v_lshlrev_b64 v[134:135], 11, v[132:133]
	v_readlane_b32 s3, v245, 58
	v_lshlrev_b64 v[162:163], 1, v[130:131]
	s_barrier
	v_lshl_add_u64 v[134:135], s[2:3], 0, v[134:135]
	v_lshl_add_u64 v[138:139], v[134:135], 0, v[162:163]
	s_nop 1
	v_subrev_u32_e32 v175, s2, v138
	global_load_dwordx4 v[176:179], v175, s[2:3] nt
	global_load_dwordx4 v[180:183], v175, s[2:3] offset:256 nt
	s_add_u32 s100, s2, 0x8000
	s_addc_u32 s101, s3, 0
	global_load_dwordx4 v[184:187], v175, s[100:101] nt
	global_load_dwordx4 v[188:191], v175, s[100:101] offset:256 nt
	s_add_u32 s98, s2, 0x10000
	s_addc_u32 s99, s3, 0
	global_load_dwordx4 v[192:195], v175, s[98:99] nt
	global_load_dwordx4 v[196:199], v175, s[98:99] offset:256 nt
	s_add_u32 s100, s2, 0x18000
	s_addc_u32 s101, s3, 0
	global_load_dwordx4 v[200:203], v175, s[100:101] nt
	global_load_dwordx4 v[204:207], v175, s[100:101] offset:256 nt
	s_add_u32 s98, s2, 0x40000
	s_addc_u32 s99, s3, 0
	global_load_dwordx4 v[208:211], v175, s[98:99] nt
	global_load_dwordx4 v[212:215], v175, s[98:99] offset:256 nt
	s_add_u32 s100, s2, 0x48000
	s_addc_u32 s101, s3, 0
	global_load_dwordx4 v[216:219], v175, s[100:101] nt
	global_load_dwordx4 v[220:223], v175, s[100:101] offset:256 nt
	s_add_u32 s98, s2, 0x50000
	s_addc_u32 s99, s3, 0
	global_load_dwordx4 v[224:227], v175, s[98:99] nt
	global_load_dwordx4 v[228:231], v175, s[98:99] offset:256 nt
	s_add_u32 s100, s2, 0x58000
	s_addc_u32 s101, s3, 0
	global_load_dwordx4 v[232:235], v175, s[100:101] nt
	global_load_dwordx4 v[236:239], v175, s[100:101] offset:256 nt
	s_nop 0
	v_or_b32_e32 v142, 16, v132
	v_ashrrev_i32_e32 v143, 31, v142
	v_lshlrev_b64 v[142:143], 11, v[142:143]
	s_mov_b32 s0, 0x3f9837f0
	v_lshl_add_u64 v[142:143], s[2:3], 0, v[142:143]
	v_lshl_add_u64 v[142:143], v[142:143], 0, v[162:163]
	v_mbcnt_hi_u32_b32 v133, -1, v1
	s_waitcnt vmcnt(14)
	v_lshlrev_b32_e32 v144, 16, v176
	v_and_b32_e32 v145, 0xffff0000, v176
	v_lshlrev_b32_e32 v134, 16, v177
	v_and_b32_e32 v135, 0xffff0000, v177
	v_lshlrev_b32_e32 v146, 16, v178
	v_and_b32_e32 v147, 0xffff0000, v178
	v_lshlrev_b32_e32 v136, 16, v179
	v_and_b32_e32 v137, 0xffff0000, v179
	v_lshlrev_b32_e32 v148, 16, v180
	v_and_b32_e32 v149, 0xffff0000, v180
	v_lshlrev_b32_e32 v138, 16, v181
	v_and_b32_e32 v139, 0xffff0000, v181
	v_lshlrev_b32_e32 v152, 16, v182
	v_and_b32_e32 v153, 0xffff0000, v182
	v_lshlrev_b32_e32 v140, 16, v183
	v_and_b32_e32 v141, 0xffff0000, v183
	v_pk_fma_f32 v[96:97], v[134:135], s[0:1], v[96:97] op_sel_hi:[1,0,1]
	v_pk_fma_f32 v[94:95], v[144:145], s[0:1], v[94:95] op_sel_hi:[1,0,1]
	v_pk_fma_f32 v[104:105], v[136:137], s[0:1], v[104:105] op_sel_hi:[1,0,1]
	v_pk_fma_f32 v[102:103], v[146:147], s[0:1], v[102:103] op_sel_hi:[1,0,1]
	v_pk_fma_f32 v[92:93], v[138:139], s[0:1], v[92:93] op_sel_hi:[1,0,1]
	v_pk_fma_f32 v[90:91], v[148:149], s[0:1], v[90:91] op_sel_hi:[1,0,1]
	v_pk_fma_f32 v[76:77], v[140:141], s[0:1], v[76:77] op_sel_hi:[1,0,1]
	v_pk_fma_f32 v[74:75], v[152:153], s[0:1], v[74:75] op_sel_hi:[1,0,1]
	s_nop 0
	v_or_b32_e32 v142, 32, v132
	v_ashrrev_i32_e32 v143, 31, v142
	v_lshlrev_b64 v[142:143], 11, v[142:143]
	v_lshl_add_u64 v[142:143], s[2:3], 0, v[142:143]
	v_lshl_add_u64 v[142:143], v[142:143], 0, v[162:163]
	s_waitcnt vmcnt(13)
	v_lshlrev_b32_e32 v144, 16, v184
	v_and_b32_e32 v145, 0xffff0000, v184
	v_lshlrev_b32_e32 v134, 16, v185
	v_and_b32_e32 v135, 0xffff0000, v185
	v_lshlrev_b32_e32 v146, 16, v186
	v_and_b32_e32 v147, 0xffff0000, v186
	v_lshlrev_b32_e32 v136, 16, v187
	v_and_b32_e32 v137, 0xffff0000, v187
	s_waitcnt vmcnt(12)
	v_lshlrev_b32_e32 v148, 16, v188
	v_and_b32_e32 v149, 0xffff0000, v188
	v_lshlrev_b32_e32 v138, 16, v189
	v_and_b32_e32 v139, 0xffff0000, v189
	v_lshlrev_b32_e32 v152, 16, v190
	v_and_b32_e32 v153, 0xffff0000, v190
	v_lshlrev_b32_e32 v140, 16, v191
	v_and_b32_e32 v141, 0xffff0000, v191
	v_pk_fma_f32 v[108:109], v[134:135], s[0:1], v[108:109] op_sel_hi:[1,0,1]
	v_pk_fma_f32 v[106:107], v[144:145], s[0:1], v[106:107] op_sel_hi:[1,0,1]
	v_pk_fma_f32 v[112:113], v[136:137], s[0:1], v[112:113] op_sel_hi:[1,0,1]
	v_pk_fma_f32 v[110:111], v[146:147], s[0:1], v[110:111] op_sel_hi:[1,0,1]
	v_pk_fma_f32 v[80:81], v[138:139], s[0:1], v[80:81] op_sel_hi:[1,0,1]
	v_pk_fma_f32 v[78:79], v[148:149], s[0:1], v[78:79] op_sel_hi:[1,0,1]
	v_pk_fma_f32 v[68:69], v[140:141], s[0:1], v[68:69] op_sel_hi:[1,0,1]
	v_pk_fma_f32 v[66:67], v[152:153], s[0:1], v[66:67] op_sel_hi:[1,0,1]
	s_nop 0
	v_or_b32_e32 v142, 48, v132
	v_ashrrev_i32_e32 v143, 31, v142
	v_lshlrev_b64 v[142:143], 11, v[142:143]
	v_lshl_add_u64 v[142:143], s[2:3], 0, v[142:143]
	v_lshl_add_u64 v[142:143], v[142:143], 0, v[162:163]
	s_waitcnt vmcnt(11)
	v_lshlrev_b32_e32 v144, 16, v192
	v_and_b32_e32 v145, 0xffff0000, v192
	v_lshlrev_b32_e32 v134, 16, v193
	v_and_b32_e32 v135, 0xffff0000, v193
	v_lshlrev_b32_e32 v146, 16, v194
	v_and_b32_e32 v147, 0xffff0000, v194
	v_lshlrev_b32_e32 v136, 16, v195
	v_and_b32_e32 v137, 0xffff0000, v195
	s_waitcnt vmcnt(10)
;     __device__ __forceinline__ void fused(f32x4 (&acc)[2][2][4][2], const Unit& u, int wr, int wc, int fr, int fq, PG8_LAS unsigned char* lds, int wid, int lane) const {
;     ...
;             for (int m = 0; m < 4; ++m) { const size_t off = (size_t)(u.pm * BM + ai * HALF + wr * 64 + m * 16 + fr) * ldc + col0;
; #pragma unroll
;                 for (int bj = 0; bj < 2; ++bj) { f32x4 b0, b1;
;                     if (base) { b0 = *(const f32x4*)(base + off + bj * HALF); b1 = *(const f32x4*)(base + off + bj * HALF + 4); }
;                     else { const u32x4 w = *(const u32x4*)(baseb + off + bj * HALF);
;                         b0 = (f32x4){__uint_as_float(w.x << 16), __uint_as_float(w.x & 0xffff0000u), __uint_as_float(w.y << 16), __uint_as_float(w.y & 0xffff0000u)};
;                         b1 = (f32x4){__uint_as_float(w.z << 16), __uint_as_float(w.z & 0xffff0000u), __uint_as_float(w.w << 16), __uint_as_float(w.w & 0xffff0000u)}; }
;                     acc[ai][bj][m][0] = acc[ai][bj][m][0] * s + b0 * alpha; acc[ai][bj][m][1] = acc[ai][bj][m][1] * s + b1 * alpha; }
	v_lshlrev_b32_e32 v148, 16, v196
	v_and_b32_e32 v149, 0xffff0000, v196
	v_lshlrev_b32_e32 v138, 16, v197
	v_and_b32_e32 v139, 0xffff0000, v197
	v_lshlrev_b32_e32 v152, 16, v198
	v_and_b32_e32 v153, 0xffff0000, v198
	v_lshlrev_b32_e32 v140, 16, v199
	v_and_b32_e32 v141, 0xffff0000, v199
	v_pk_fma_f32 v[116:117], v[134:135], s[0:1], v[116:117] op_sel_hi:[1,0,1]
	v_pk_fma_f32 v[114:115], v[144:145], s[0:1], v[114:115] op_sel_hi:[1,0,1]
	v_pk_fma_f32 v[124:125], v[136:137], s[0:1], v[124:125] op_sel_hi:[1,0,1]
	v_pk_fma_f32 v[122:123], v[146:147], s[0:1], v[122:123] op_sel_hi:[1,0,1]
	v_pk_fma_f32 v[100:101], v[138:139], s[0:1], v[100:101] op_sel_hi:[1,0,1]
	v_pk_fma_f32 v[98:99], v[148:149], s[0:1], v[98:99] op_sel_hi:[1,0,1]
	v_pk_fma_f32 v[88:89], v[140:141], s[0:1], v[88:89] op_sel_hi:[1,0,1]
	v_pk_fma_f32 v[86:87], v[152:153], s[0:1], v[86:87] op_sel_hi:[1,0,1]
	s_nop 0
	v_add_u32_e32 v142, 0x80, v132
	v_ashrrev_i32_e32 v143, 31, v142
	v_lshlrev_b64 v[142:143], 11, v[142:143]
	v_lshl_add_u64 v[142:143], s[2:3], 0, v[142:143]
	v_lshl_add_u64 v[142:143], v[142:143], 0, v[162:163]
	s_waitcnt vmcnt(9)
	v_lshlrev_b32_e32 v144, 16, v200
	v_and_b32_e32 v145, 0xffff0000, v200
	v_lshlrev_b32_e32 v134, 16, v201
	v_and_b32_e32 v135, 0xffff0000, v201
	v_lshlrev_b32_e32 v146, 16, v202
	v_and_b32_e32 v147, 0xffff0000, v202
	v_lshlrev_b32_e32 v136, 16, v203
	v_and_b32_e32 v137, 0xffff0000, v203
	s_waitcnt vmcnt(8)
	v_lshlrev_b32_e32 v148, 16, v204
	v_and_b32_e32 v149, 0xffff0000, v204
	v_lshlrev_b32_e32 v138, 16, v205
	v_and_b32_e32 v139, 0xffff0000, v205
	v_lshlrev_b32_e32 v152, 16, v206
	v_and_b32_e32 v153, 0xffff0000, v206
	v_lshlrev_b32_e32 v140, 16, v207
	v_and_b32_e32 v141, 0xffff0000, v207
	v_pk_fma_f32 v[128:129], v[134:135], s[0:1], v[128:129] op_sel_hi:[1,0,1]
	v_pk_fma_f32 v[126:127], v[144:145], s[0:1], v[126:127] op_sel_hi:[1,0,1]
	v_pk_fma_f32 v[120:121], v[136:137], s[0:1], v[120:121] op_sel_hi:[1,0,1]
	v_pk_fma_f32 v[118:119], v[146:147], s[0:1], v[118:119] op_sel_hi:[1,0,1]
	v_pk_fma_f32 v[84:85], v[138:139], s[0:1], v[84:85] op_sel_hi:[1,0,1]
	v_pk_fma_f32 v[82:83], v[148:149], s[0:1], v[82:83] op_sel_hi:[1,0,1]
	v_pk_fma_f32 v[72:73], v[140:141], s[0:1], v[72:73] op_sel_hi:[1,0,1]
	v_pk_fma_f32 v[70:71], v[152:153], s[0:1], v[70:71] op_sel_hi:[1,0,1]
	s_nop 0
	v_add_u32_e32 v142, 0x90, v132
	v_ashrrev_i32_e32 v143, 31, v142
	v_lshlrev_b64 v[142:143], 11, v[142:143]
	v_lshl_add_u64 v[142:143], s[2:3], 0, v[142:143]
	v_lshl_add_u64 v[142:143], v[142:143], 0, v[162:163]
	s_waitcnt vmcnt(7)
	v_lshlrev_b32_e32 v144, 16, v208
	v_and_b32_e32 v145, 0xffff0000, v208
	v_lshlrev_b32_e32 v134, 16, v209
	v_and_b32_e32 v135, 0xffff0000, v209
	v_lshlrev_b32_e32 v146, 16, v210
	v_and_b32_e32 v147, 0xffff0000, v210
	v_lshlrev_b32_e32 v136, 16, v211
	v_and_b32_e32 v137, 0xffff0000, v211
	s_waitcnt vmcnt(6)
	v_lshlrev_b32_e32 v148, 16, v212
	v_and_b32_e32 v149, 0xffff0000, v212
	v_lshlrev_b32_e32 v138, 16, v213
	v_and_b32_e32 v139, 0xffff0000, v213
	v_lshlrev_b32_e32 v152, 16, v214
	v_and_b32_e32 v153, 0xffff0000, v214
	v_lshlrev_b32_e32 v140, 16, v215
	v_and_b32_e32 v141, 0xffff0000, v215
	v_pk_fma_f32 v[64:65], v[134:135], s[0:1], v[64:65] op_sel_hi:[1,0,1]
	v_pk_fma_f32 v[62:63], v[144:145], s[0:1], v[62:63] op_sel_hi:[1,0,1]
	v_pk_fma_f32 v[60:61], v[136:137], s[0:1], v[60:61] op_sel_hi:[1,0,1]
	v_pk_fma_f32 v[58:59], v[146:147], s[0:1], v[58:59] op_sel_hi:[1,0,1]
	v_pk_fma_f32 v[56:57], v[138:139], s[0:1], v[56:57] op_sel_hi:[1,0,1]
	v_pk_fma_f32 v[54:55], v[148:149], s[0:1], v[54:55] op_sel_hi:[1,0,1]
	v_pk_fma_f32 v[52:53], v[140:141], s[0:1], v[52:53] op_sel_hi:[1,0,1]
	v_pk_fma_f32 v[50:51], v[152:153], s[0:1], v[50:51] op_sel_hi:[1,0,1]
	s_nop 0
	v_add_u32_e32 v142, 0xa0, v132
	v_ashrrev_i32_e32 v143, 31, v142
	v_lshlrev_b64 v[142:143], 11, v[142:143]
	v_lshl_add_u64 v[142:143], s[2:3], 0, v[142:143]
	v_lshl_add_u64 v[142:143], v[142:143], 0, v[162:163]
	s_waitcnt vmcnt(5)
	v_lshlrev_b32_e32 v144, 16, v216
	v_and_b32_e32 v145, 0xffff0000, v216
	v_lshlrev_b32_e32 v134, 16, v217
	v_and_b32_e32 v135, 0xffff0000, v217
	v_lshlrev_b32_e32 v146, 16, v218
	v_and_b32_e32 v147, 0xffff0000, v218
	v_lshlrev_b32_e32 v136, 16, v219
	v_and_b32_e32 v137, 0xffff0000, v219
	s_waitcnt vmcnt(4)
	v_lshlrev_b32_e32 v148, 16, v220
	v_and_b32_e32 v149, 0xffff0000, v220
	v_lshlrev_b32_e32 v138, 16, v221
	v_and_b32_e32 v139, 0xffff0000, v221
	v_lshlrev_b32_e32 v152, 16, v222
	v_and_b32_e32 v153, 0xffff0000, v222
	v_lshlrev_b32_e32 v140, 16, v223
	v_and_b32_e32 v141, 0xffff0000, v223
	v_pk_fma_f32 v[48:49], v[134:135], s[0:1], v[48:49] op_sel_hi:[1,0,1]
	v_pk_fma_f32 v[46:47], v[144:145], s[0:1], v[46:47] op_sel_hi:[1,0,1]
	v_pk_fma_f32 v[44:45], v[136:137], s[0:1], v[44:45] op_sel_hi:[1,0,1]
	v_pk_fma_f32 v[42:43], v[146:147], s[0:1], v[42:43] op_sel_hi:[1,0,1]
	v_pk_fma_f32 v[40:41], v[138:139], s[0:1], v[40:41] op_sel_hi:[1,0,1]
	v_pk_fma_f32 v[38:39], v[148:149], s[0:1], v[38:39] op_sel_hi:[1,0,1]
	v_pk_fma_f32 v[36:37], v[140:141], s[0:1], v[36:37] op_sel_hi:[1,0,1]
	v_pk_fma_f32 v[34:35], v[152:153], s[0:1], v[34:35] op_sel_hi:[1,0,1]
	v_mov_b32_e32 v146, v95
	v_and_b32_e32 v142, 64, v133
	v_xor_b32_e32 v143, 16, v133
	v_add_u32_e32 v158, 64, v142
	v_add_u32_e32 v142, 0xb0, v132
	v_cmp_lt_i32_e32 vcc, v143, v158
	v_mov_b32_e32 v147, v96
	v_mov_b32_e32 v148, v94
	v_cndmask_b32_e32 v132, v133, v143, vcc
	v_ashrrev_i32_e32 v143, 31, v142
	v_lshlrev_b64 v[142:143], 11, v[142:143]
	v_lshl_add_u64 v[142:143], s[2:3], 0, v[142:143]
	v_lshl_add_u64 v[142:143], v[142:143], 0, v[162:163]
	v_mov_b32_e32 v149, v97
	v_pk_add_f32 v[146:147], v[146:147], v[148:149]
	v_lshlrev_b32_e32 v132, 2, v132
	v_add_f32_e32 v146, v146, v147
	s_waitcnt vmcnt(3)
;     __device__ __forceinline__ bool run(const f32x4 (&v)[2][2][4][2], const Unit& u, int wr, int wc, int fr, int fq, PG8_LAS unsigned char* lds, int wid, int lane) const {
;     ...
;                     for (int n = 0; n < 2; ++n) { const f32x4 x = v[ai][bj][m][n]; s += (x[0] + x[1]) + (x[2] + x[3]); }
;                 s += __shfl_xor(s, 16); s += __shfl_xor(s, 32);
;                 const float mw = s * (1.0f / 64.0f); float q = 0.f;
; #pragma unroll
;                 for (int bj = 0; bj < 2; ++bj)
; #pragma unroll
;                     for (int n = 0; n < 2; ++n) { const f32x4 d = v[ai][bj][m][n] - mw; q += (d[0] * d[0] + d[1] * d[1]) + (d[2] * d[2] + d[3] * d[3]); }
;                 q += __shfl_xor(q, 16); q += __shfl_xor(q, 32);
;                 if (fq == 0) P[(ai * HALF + wr * 64 + m * 16 + fr) * 4 + wc] = (f32x2v){mw, q};
;     __device__ __forceinline__ void fused(f32x4 (&acc)[2][2][4][2], const Unit& u, int wr, int wc, int fr, int fq, PG8_LAS unsigned char* lds, int wid, int lane) const {
;     ...
;             for (int m = 0; m < 4; ++m) { const size_t off = (size_t)(u.pm * BM + ai * HALF + wr * 64 + m * 16 + fr) * ldc + col0;
; #pragma unroll
;                 for (int bj = 0; bj < 2; ++bj) { f32x4 b0, b1;
;                     if (base) { b0 = *(const f32x4*)(base + off + bj * HALF); b1 = *(const f32x4*)(base + off + bj * HALF + 4); }
;                     else { const u32x4 w = *(const u32x4*)(baseb + off + bj * HALF);
;                         b0 = (f32x4){__uint_as_float(w.x << 16), __uint_as_float(w.x & 0xffff0000u), __uint_as_float(w.y << 16), __uint_as_float(w.y & 0xffff0000u)};
;                         b1 = (f32x4){__uint_as_float(w.z << 16), __uint_as_float(w.z & 0xffff0000u), __uint_as_float(w.w << 16), __uint_as_float(w.w & 0xffff0000u)}; }
;                     acc[ai][bj][m][0] = acc[ai][bj][m][0] * s + b0 * alpha; acc[ai][bj][m][1] = acc[ai][bj][m][1] * s + b1 * alpha; }
	v_lshlrev_b32_e32 v144, 16, v224
	v_and_b32_e32 v145, 0xffff0000, v224
	v_lshlrev_b32_e32 v134, 16, v225
	v_and_b32_e32 v135, 0xffff0000, v225
	v_lshlrev_b32_e32 v152, 16, v226
	v_and_b32_e32 v153, 0xffff0000, v226
	v_lshlrev_b32_e32 v136, 16, v227
	v_and_b32_e32 v137, 0xffff0000, v227
	s_waitcnt vmcnt(2)
	v_lshlrev_b32_e32 v154, 16, v228
	v_and_b32_e32 v155, 0xffff0000, v228
	v_lshlrev_b32_e32 v138, 16, v229
	v_and_b32_e32 v139, 0xffff0000, v229
	v_lshlrev_b32_e32 v156, 16, v230
	v_and_b32_e32 v157, 0xffff0000, v230
	v_lshlrev_b32_e32 v140, 16, v231
	v_and_b32_e32 v141, 0xffff0000, v231
	v_pk_fma_f32 v[32:33], v[134:135], s[0:1], v[32:33] op_sel_hi:[1,0,1]
	v_pk_fma_f32 v[30:31], v[144:145], s[0:1], v[30:31] op_sel_hi:[1,0,1]
	v_pk_fma_f32 v[28:29], v[136:137], s[0:1], v[28:29] op_sel_hi:[1,0,1]
	v_pk_fma_f32 v[26:27], v[152:153], s[0:1], v[26:27] op_sel_hi:[1,0,1]
	v_pk_fma_f32 v[24:25], v[138:139], s[0:1], v[24:25] op_sel_hi:[1,0,1]
	v_pk_fma_f32 v[22:23], v[154:155], s[0:1], v[22:23] op_sel_hi:[1,0,1]
	v_pk_fma_f32 v[20:21], v[140:141], s[0:1], v[20:21] op_sel_hi:[1,0,1]
	v_pk_fma_f32 v[18:19], v[156:157], s[0:1], v[18:19] op_sel_hi:[1,0,1]
	v_mov_b32_e32 v134, v103
	v_mov_b32_e32 v135, v104
	v_mov_b32_e32 v136, v102
	v_mov_b32_e32 v137, v105
	v_pk_add_f32 v[134:135], v[134:135], v[136:137]
	v_add_f32_e32 v153, v90, v91
	v_pk_add_f32 v[134:135], v[134:135], v[134:135] op_sel_hi:[0,1]
	v_add_f32_e32 v155, v92, v93
	v_mov_b32_e32 v152, v74
	v_mov_b32_e32 v154, v75
	v_mov_b32_e32 v156, v77
	v_add_f32_e32 v157, 0, v146
	v_mov_b32_e32 v134, v76
	v_pk_add_f32 v[136:137], v[152:153], v[154:155]
	v_pk_add_f32 v[134:135], v[134:135], v[156:157]
	s_nop 0
	v_pk_add_f32 v[134:135], v[136:137], v[134:135]
	v_xor_b32_e32 v136, 32, v133
	v_add_f32_e32 v134, v134, v135
	v_mov_b32_e32 v135, v134
	s_nop 1
	v_permlane16_swap_b32 v134, v135
	v_cmp_lt_i32_e32 vcc, v136, v158
	s_waitcnt lgkmcnt(0)
	v_add_f32_e32 v134, v134, v135
	v_cndmask_b32_e32 v133, v133, v136, vcc
	v_lshlrev_b32_e32 v133, 2, v133
	v_mov_b32_e32 v135, v134
	s_nop 1
	v_permlane32_swap_b32 v134, v135
	s_waitcnt lgkmcnt(0)
	v_add_f32_e32 v135, v134, v135
	v_fmamk_f32 v136, v135, 0xbc800000, v97
	v_fmamk_f32 v146, v135, 0xbc800000, v95
	v_fmamk_f32 v148, v135, 0xbc800000, v105
	v_fmamk_f32 v152, v135, 0xbc800000, v103
	v_fmamk_f32 v134, v135, 0xbc800000, v96
	v_fmamk_f32 v137, v135, 0xbc800000, v94
	v_fmamk_f32 v147, v135, 0xbc800000, v104
	v_fmamk_f32 v149, v135, 0xbc800000, v102
	v_fmamk_f32 v154, v135, 0xbc800000, v93
	v_fmamk_f32 v156, v135, 0xbc800000, v91
	v_mul_f32_e32 v146, v146, v146
	v_mul_f32_e32 v136, v136, v136
	v_mul_f32_e32 v152, v152, v152
	v_mul_f32_e32 v148, v148, v148
	v_fmamk_f32 v153, v135, 0xbc800000, v92
	v_fmamk_f32 v155, v135, 0xbc800000, v90
	v_fmamk_f32 v158, v135, 0xbc800000, v77
	v_fmamk_f32 v160, v135, 0xbc800000, v75
	v_mul_f32_e32 v156, v156, v156
	v_mul_f32_e32 v154, v154, v154
	v_fmac_f32_e32 v146, v137, v137
	v_fmac_f32_e32 v136, v134, v134
	v_fmac_f32_e32 v152, v149, v149
	v_fmac_f32_e32 v148, v147, v147
	v_fmamk_f32 v157, v135, 0xbc800000, v76
	v_fmamk_f32 v159, v135, 0xbc800000, v74
	v_mul_f32_e32 v160, v160, v160
	v_mul_f32_e32 v158, v158, v158
	v_fmac_f32_e32 v156, v155, v155
	v_fmac_f32_e32 v154, v153, v153
	v_add_f32_e32 v134, v146, v136
	v_add_f32_e32 v136, v152, v148
	v_fmac_f32_e32 v160, v159, v159
	v_fmac_f32_e32 v158, v157, v157
	v_add_f32_e32 v137, v156, v154
	v_add_f32_e32 v134, v134, v136
	v_add_f32_e32 v146, v160, v158
	v_add_f32_e32 v134, v137, v134
	v_add_f32_e32 v136, v146, v134
	v_mov_b32_e32 v137, v136
	s_nop 1
	v_permlane16_swap_b32 v136, v137
	v_and_b32_e32 v134, 63, v150
	v_cmp_gt_u32_e32 vcc, 16, v134
	s_waitcnt lgkmcnt(0)
	v_add_f32_e32 v136, v136, v137
	v_mov_b32_e32 v137, v136
	s_nop 1
	v_permlane32_swap_b32 v136, v137
	s_waitcnt vmcnt(1)
	v_lshlrev_b32_e32 v146, 16, v232
	v_and_b32_e32 v147, 0xffff0000, v232
	v_lshlrev_b32_e32 v138, 16, v233
	v_and_b32_e32 v139, 0xffff0000, v233
	v_lshlrev_b32_e32 v148, 16, v234
	v_and_b32_e32 v149, 0xffff0000, v234
	v_lshlrev_b32_e32 v140, 16, v235
	v_and_b32_e32 v141, 0xffff0000, v235
	s_waitcnt vmcnt(0)
	v_lshlrev_b32_e32 v152, 16, v236
	v_and_b32_e32 v153, 0xffff0000, v236
	v_lshlrev_b32_e32 v142, 16, v237
	v_and_b32_e32 v143, 0xffff0000, v237
	v_lshlrev_b32_e32 v154, 16, v238
	v_and_b32_e32 v155, 0xffff0000, v238
	v_lshlrev_b32_e32 v144, 16, v239
	v_and_b32_e32 v145, 0xffff0000, v239
	v_pk_fma_f32 v[16:17], v[138:139], s[0:1], v[16:17] op_sel_hi:[1,0,1]
	v_pk_fma_f32 v[14:15], v[146:147], s[0:1], v[14:15] op_sel_hi:[1,0,1]
	v_pk_fma_f32 v[12:13], v[140:141], s[0:1], v[12:13] op_sel_hi:[1,0,1]
	v_pk_fma_f32 v[10:11], v[148:149], s[0:1], v[10:11] op_sel_hi:[1,0,1]
	v_pk_fma_f32 v[8:9], v[142:143], s[0:1], v[8:9] op_sel_hi:[1,0,1]
	v_pk_fma_f32 v[6:7], v[152:153], s[0:1], v[6:7] op_sel_hi:[1,0,1]
	v_pk_fma_f32 v[4:5], v[144:145], s[0:1], v[4:5] op_sel_hi:[1,0,1]
	v_pk_fma_f32 v[2:3], v[154:155], s[0:1], v[2:3] op_sel_hi:[1,0,1]
	s_lshl_b32 s0, s13, 3
	s_add_i32 s2, s0, 0
	s_and_saveexec_b64 s[0:1], vcc
	s_cbranch_execz .LBB0_1498
	s_lshl_b32 s3, s17, 11
	s_add_i32 s3, s2, s3
	v_mul_f32_e32 v138, 0x3c800000, v135
	v_lshl_add_u32 v135, v151, 5, s3
	s_waitcnt lgkmcnt(0)
	v_add_f32_e32 v139, v136, v137
	ds_write_b64 v135, v[138:139]

;     __device__ __forceinline__ void fused(f32x4 (&acc)[2][2][4][2], const Unit& u, int wr, int wc, int fr, int fq, PG8_LAS unsigned char* lds, int wid, int lane) const {
;     ...
;             for (int m = 0; m < 4; ++m) { const size_t off = (size_t)(u.pm * BM + ai * HALF + wr * 64 + m * 16 + fr) * ldc + col0;
; #pragma unroll
;                 for (int bj = 0; bj < 2; ++bj) { f32x4 b0, b1;
;                     if (base) { b0 = *(const f32x4*)(base + off + bj * HALF); b1 = *(const f32x4*)(base + off + bj * HALF + 4); }
;                     else { const u32x4 w = *(const u32x4*)(baseb + off + bj * HALF);
;                         b0 = (f32x4){__uint_as_float(w.x << 16), __uint_as_float(w.x & 0xffff0000u), __uint_as_float(w.y << 16), __uint_as_float(w.y & 0xffff0000u)};
;                         b1 = (f32x4){__uint_as_float(w.z << 16), __uint_as_float(w.z & 0xffff0000u), __uint_as_float(w.w << 16), __uint_as_float(w.w & 0xffff0000u)}; }
;                     acc[ai][bj][m][0] = acc[ai][bj][m][0] * s + b0 * alpha; acc[ai][bj][m][1] = acc[ai][bj][m][1] * s + b1 * alpha; }
.LBB0_1713:
	s_lshl_b32 s0, s27, 5
	s_lshl_b32 s1, s12, 8
	v_lshrrev_b32_e32 v130, 1, v150
	s_or_b32 s0, s1, s0
	s_lshl_b32 s18, s25, 8
	v_and_or_b32 v130, v130, 24, s0
	s_add_i32 s0, s18, s35
	v_or_b32_e32 v132, s0, v151
	v_ashrrev_i32_e32 v133, 31, v132
	v_ashrrev_i32_e32 v131, 31, v130
	v_lshlrev_b64 v[134:135], 11, v[132:133]
	v_lshl_add_u64 v[136:137], s[10:11], 0, v[134:135]
	v_lshlrev_b64 v[134:135], 1, v[130:131]
	v_lshl_add_u64 v[140:141], v[136:137], 0, v[134:135]
	s_barrier
	s_nop 1
	v_subrev_u32_e32 v175, s10, v140
	global_load_dwordx4 v[176:179], v175, s[10:11] nt
	global_load_dwordx4 v[180:183], v175, s[10:11] offset:256 nt
	s_add_u32 s100, s10, 0x8000
	s_addc_u32 s101, s11, 0
	global_load_dwordx4 v[184:187], v175, s[100:101] nt
	global_load_dwordx4 v[188:191], v175, s[100:101] offset:256 nt
	s_add_u32 s98, s10, 0x10000
	s_addc_u32 s99, s11, 0
	global_load_dwordx4 v[192:195], v175, s[98:99] nt
	global_load_dwordx4 v[196:199], v175, s[98:99] offset:256 nt
	s_add_u32 s100, s10, 0x18000
	s_addc_u32 s101, s11, 0
	global_load_dwordx4 v[200:203], v175, s[100:101] nt
	global_load_dwordx4 v[204:207], v175, s[100:101] offset:256 nt
	s_add_u32 s98, s10, 0x40000
	s_addc_u32 s99, s11, 0
	global_load_dwordx4 v[208:211], v175, s[98:99] nt
	global_load_dwordx4 v[212:215], v175, s[98:99] offset:256 nt
	s_add_u32 s100, s10, 0x48000
	s_addc_u32 s101, s11, 0
	global_load_dwordx4 v[216:219], v175, s[100:101] nt
	global_load_dwordx4 v[220:223], v175, s[100:101] offset:256 nt
	s_add_u32 s98, s10, 0x50000
	s_addc_u32 s99, s11, 0
	global_load_dwordx4 v[224:227], v175, s[98:99] nt
	global_load_dwordx4 v[228:231], v175, s[98:99] offset:256 nt
	s_add_u32 s100, s10, 0x58000
	s_addc_u32 s101, s11, 0
	global_load_dwordx4 v[232:235], v175, s[100:101] nt
	global_load_dwordx4 v[236:239], v175, s[100:101] offset:256 nt
	s_nop 0
	v_or_b32_e32 v144, 16, v132
	v_ashrrev_i32_e32 v145, 31, v144
	s_mov_b32 s0, 0x3f9837f0
	v_lshlrev_b64 v[144:145], 11, v[144:145]
	v_lshl_add_u64 v[144:145], s[10:11], 0, v[144:145]
	v_lshl_add_u64 v[144:145], v[144:145], 0, v[134:135]
	v_mbcnt_hi_u32_b32 v156, -1, v1
	v_and_b32_e32 v133, 64, v156
	v_add_u32_e32 v157, 64, v133
	v_xor_b32_e32 v1, 16, v156
	v_cmp_lt_i32_e32 vcc, v1, v157
	s_waitcnt vmcnt(14)
	v_lshlrev_b32_e32 v146, 16, v176
	v_and_b32_e32 v147, 0xffff0000, v176
	v_lshlrev_b32_e32 v136, 16, v177
	v_and_b32_e32 v137, 0xffff0000, v177
	v_lshlrev_b32_e32 v148, 16, v178
	v_and_b32_e32 v149, 0xffff0000, v178
	v_lshlrev_b32_e32 v138, 16, v179
	v_and_b32_e32 v139, 0xffff0000, v179
	v_lshlrev_b32_e32 v152, 16, v180
	v_and_b32_e32 v153, 0xffff0000, v180
	v_lshlrev_b32_e32 v140, 16, v181
	v_and_b32_e32 v141, 0xffff0000, v181
	v_lshlrev_b32_e32 v154, 16, v182
	v_and_b32_e32 v155, 0xffff0000, v182
	v_lshlrev_b32_e32 v142, 16, v183
	v_and_b32_e32 v143, 0xffff0000, v183
	v_pk_mul_f32 v[146:147], v[146:147], s[0:1] op_sel_hi:[1,0]
	v_pk_mul_f32 v[136:137], v[136:137], s[0:1] op_sel_hi:[1,0]
	v_pk_mul_f32 v[148:149], v[148:149], s[0:1] op_sel_hi:[1,0]
	v_pk_mul_f32 v[138:139], v[138:139], s[0:1] op_sel_hi:[1,0]
	v_pk_mul_f32 v[152:153], v[152:153], s[0:1] op_sel_hi:[1,0]
	v_pk_mul_f32 v[140:141], v[140:141], s[0:1] op_sel_hi:[1,0]
	v_pk_mul_f32 v[154:155], v[154:155], s[0:1] op_sel_hi:[1,0]
	v_pk_mul_f32 v[142:143], v[142:143], s[0:1] op_sel_hi:[1,0]
	v_pk_fma_f32 v[72:73], v[72:73], 0.5, v[136:137] op_sel_hi:[1,0,1]
	v_pk_fma_f32 v[70:71], v[70:71], 0.5, v[146:147] op_sel_hi:[1,0,1]
	v_pk_fma_f32 v[80:81], v[80:81], 0.5, v[138:139] op_sel_hi:[1,0,1]
	v_pk_fma_f32 v[78:79], v[78:79], 0.5, v[148:149] op_sel_hi:[1,0,1]
	v_pk_fma_f32 v[68:69], v[68:69], 0.5, v[140:141] op_sel_hi:[1,0,1]
	v_pk_fma_f32 v[66:67], v[66:67], 0.5, v[152:153] op_sel_hi:[1,0,1]
	v_pk_fma_f32 v[76:77], v[76:77], 0.5, v[142:143] op_sel_hi:[1,0,1]
	v_pk_fma_f32 v[74:75], v[74:75], 0.5, v[154:155] op_sel_hi:[1,0,1]
	v_cndmask_b32_e32 v1, v156, v1, vcc
	v_or_b32_e32 v144, 32, v132
	v_ashrrev_i32_e32 v145, 31, v144
	v_lshlrev_b64 v[144:145], 11, v[144:145]
	v_lshl_add_u64 v[144:145], s[10:11], 0, v[144:145]
	v_lshl_add_u64 v[144:145], v[144:145], 0, v[134:135]
	v_lshlrev_b32_e32 v1, 2, v1
	s_waitcnt vmcnt(13)
	v_lshlrev_b32_e32 v146, 16, v184
	v_and_b32_e32 v147, 0xffff0000, v184
	v_lshlrev_b32_e32 v136, 16, v185
	v_and_b32_e32 v137, 0xffff0000, v185
	v_lshlrev_b32_e32 v148, 16, v186
	v_and_b32_e32 v149, 0xffff0000, v186
	v_lshlrev_b32_e32 v138, 16, v187
	v_and_b32_e32 v139, 0xffff0000, v187
	s_waitcnt vmcnt(12)
	v_lshlrev_b32_e32 v152, 16, v188
	v_and_b32_e32 v153, 0xffff0000, v188
	v_lshlrev_b32_e32 v140, 16, v189
	v_and_b32_e32 v141, 0xffff0000, v189
	v_lshlrev_b32_e32 v154, 16, v190
	v_and_b32_e32 v155, 0xffff0000, v190
	v_lshlrev_b32_e32 v142, 16, v191
	v_and_b32_e32 v143, 0xffff0000, v191
	v_pk_mul_f32 v[146:147], v[146:147], s[0:1] op_sel_hi:[1,0]
	v_pk_mul_f32 v[136:137], v[136:137], s[0:1] op_sel_hi:[1,0]
	v_pk_mul_f32 v[148:149], v[148:149], s[0:1] op_sel_hi:[1,0]
	v_pk_mul_f32 v[138:139], v[138:139], s[0:1] op_sel_hi:[1,0]
	v_pk_mul_f32 v[152:153], v[152:153], s[0:1] op_sel_hi:[1,0]
	v_pk_mul_f32 v[140:141], v[140:141], s[0:1] op_sel_hi:[1,0]
	v_pk_mul_f32 v[154:155], v[154:155], s[0:1] op_sel_hi:[1,0]
	v_pk_mul_f32 v[142:143], v[142:143], s[0:1] op_sel_hi:[1,0]
	v_pk_fma_f32 v[96:97], v[96:97], 0.5, v[136:137] op_sel_hi:[1,0,1]
	v_pk_fma_f32 v[94:95], v[94:95], 0.5, v[146:147] op_sel_hi:[1,0,1]
	v_pk_fma_f32 v[120:121], v[120:121], 0.5, v[138:139] op_sel_hi:[1,0,1]
	v_pk_fma_f32 v[118:119], v[118:119], 0.5, v[148:149] op_sel_hi:[1,0,1]
	v_pk_fma_f32 v[84:85], v[84:85], 0.5, v[140:141] op_sel_hi:[1,0,1]
	v_pk_fma_f32 v[82:83], v[82:83], 0.5, v[152:153] op_sel_hi:[1,0,1]
	v_pk_fma_f32 v[88:89], v[88:89], 0.5, v[142:143] op_sel_hi:[1,0,1]
	v_pk_fma_f32 v[86:87], v[86:87], 0.5, v[154:155] op_sel_hi:[1,0,1]
	s_nop 0
	v_or_b32_e32 v144, 48, v132
	v_ashrrev_i32_e32 v145, 31, v144
	v_lshlrev_b64 v[144:145], 11, v[144:145]
	v_lshl_add_u64 v[144:145], s[10:11], 0, v[144:145]
	v_lshl_add_u64 v[144:145], v[144:145], 0, v[134:135]
	s_waitcnt vmcnt(11)
;     __device__ __forceinline__ void fused(f32x4 (&acc)[2][2][4][2], const Unit& u, int wr, int wc, int fr, int fq, PG8_LAS unsigned char* lds, int wid, int lane) const {
;     ...
;             for (int m = 0; m < 4; ++m) { const size_t off = (size_t)(u.pm * BM + ai * HALF + wr * 64 + m * 16 + fr) * ldc + col0;
; #pragma unroll
;                 for (int bj = 0; bj < 2; ++bj) { f32x4 b0, b1;
;                     if (base) { b0 = *(const f32x4*)(base + off + bj * HALF); b1 = *(const f32x4*)(base + off + bj * HALF + 4); }
;                     else { const u32x4 w = *(const u32x4*)(baseb + off + bj * HALF);
;                         b0 = (f32x4){__uint_as_float(w.x << 16), __uint_as_float(w.x & 0xffff0000u), __uint_as_float(w.y << 16), __uint_as_float(w.y & 0xffff0000u)};
;                         b1 = (f32x4){__uint_as_float(w.z << 16), __uint_as_float(w.z & 0xffff0000u), __uint_as_float(w.w << 16), __uint_as_float(w.w & 0xffff0000u)}; }
;                     acc[ai][bj][m][0] = acc[ai][bj][m][0] * s + b0 * alpha; acc[ai][bj][m][1] = acc[ai][bj][m][1] * s + b1 * alpha; }
	v_lshlrev_b32_e32 v146, 16, v192
	v_and_b32_e32 v147, 0xffff0000, v192
	v_lshlrev_b32_e32 v136, 16, v193
	v_and_b32_e32 v137, 0xffff0000, v193
	v_lshlrev_b32_e32 v148, 16, v194
	v_and_b32_e32 v149, 0xffff0000, v194
	v_lshlrev_b32_e32 v138, 16, v195
	v_and_b32_e32 v139, 0xffff0000, v195
	s_waitcnt vmcnt(10)
	v_lshlrev_b32_e32 v152, 16, v196
	v_and_b32_e32 v153, 0xffff0000, v196
	v_lshlrev_b32_e32 v140, 16, v197
	v_and_b32_e32 v141, 0xffff0000, v197
	v_lshlrev_b32_e32 v154, 16, v198
	v_and_b32_e32 v155, 0xffff0000, v198
	v_lshlrev_b32_e32 v142, 16, v199
	v_and_b32_e32 v143, 0xffff0000, v199
	v_pk_mul_f32 v[146:147], v[146:147], s[0:1] op_sel_hi:[1,0]
	v_pk_mul_f32 v[136:137], v[136:137], s[0:1] op_sel_hi:[1,0]
	v_pk_mul_f32 v[148:149], v[148:149], s[0:1] op_sel_hi:[1,0]
	v_pk_mul_f32 v[138:139], v[138:139], s[0:1] op_sel_hi:[1,0]
	v_pk_mul_f32 v[152:153], v[152:153], s[0:1] op_sel_hi:[1,0]
	v_pk_mul_f32 v[140:141], v[140:141], s[0:1] op_sel_hi:[1,0]
	v_pk_mul_f32 v[154:155], v[154:155], s[0:1] op_sel_hi:[1,0]
	v_pk_mul_f32 v[142:143], v[142:143], s[0:1] op_sel_hi:[1,0]
	v_pk_fma_f32 v[108:109], v[108:109], 0.5, v[136:137] op_sel_hi:[1,0,1]
	v_pk_fma_f32 v[106:107], v[106:107], 0.5, v[146:147] op_sel_hi:[1,0,1]
	v_pk_fma_f32 v[116:117], v[116:117], 0.5, v[138:139] op_sel_hi:[1,0,1]
	v_pk_fma_f32 v[114:115], v[114:115], 0.5, v[148:149] op_sel_hi:[1,0,1]
	v_pk_fma_f32 v[92:93], v[92:93], 0.5, v[140:141] op_sel_hi:[1,0,1]
	v_pk_fma_f32 v[90:91], v[90:91], 0.5, v[152:153] op_sel_hi:[1,0,1]
	v_pk_fma_f32 v[100:101], v[100:101], 0.5, v[142:143] op_sel_hi:[1,0,1]
	v_pk_fma_f32 v[98:99], v[98:99], 0.5, v[154:155] op_sel_hi:[1,0,1]
	s_nop 0
	v_add_u32_e32 v144, 0x80, v132
	v_ashrrev_i32_e32 v145, 31, v144
	v_lshlrev_b64 v[144:145], 11, v[144:145]
	v_lshl_add_u64 v[144:145], s[10:11], 0, v[144:145]
	v_lshl_add_u64 v[144:145], v[144:145], 0, v[134:135]
	s_waitcnt vmcnt(9)
	v_lshlrev_b32_e32 v146, 16, v200
	v_and_b32_e32 v147, 0xffff0000, v200
	v_lshlrev_b32_e32 v136, 16, v201
	v_and_b32_e32 v137, 0xffff0000, v201
	v_lshlrev_b32_e32 v148, 16, v202
	v_and_b32_e32 v149, 0xffff0000, v202
	v_lshlrev_b32_e32 v138, 16, v203
	v_and_b32_e32 v139, 0xffff0000, v203
	s_waitcnt vmcnt(8)
	v_lshlrev_b32_e32 v152, 16, v204
	v_and_b32_e32 v153, 0xffff0000, v204
	v_lshlrev_b32_e32 v140, 16, v205
	v_and_b32_e32 v141, 0xffff0000, v205
	v_lshlrev_b32_e32 v154, 16, v206
	v_and_b32_e32 v155, 0xffff0000, v206
	v_lshlrev_b32_e32 v142, 16, v207
	v_and_b32_e32 v143, 0xffff0000, v207
	v_pk_mul_f32 v[146:147], v[146:147], s[0:1] op_sel_hi:[1,0]
	v_pk_mul_f32 v[136:137], v[136:137], s[0:1] op_sel_hi:[1,0]
	v_pk_mul_f32 v[148:149], v[148:149], s[0:1] op_sel_hi:[1,0]
	v_pk_mul_f32 v[138:139], v[138:139], s[0:1] op_sel_hi:[1,0]
	v_pk_mul_f32 v[152:153], v[152:153], s[0:1] op_sel_hi:[1,0]
	v_pk_mul_f32 v[140:141], v[140:141], s[0:1] op_sel_hi:[1,0]
	v_pk_mul_f32 v[154:155], v[154:155], s[0:1] op_sel_hi:[1,0]
	v_pk_mul_f32 v[142:143], v[142:143], s[0:1] op_sel_hi:[1,0]
	v_pk_fma_f32 v[124:125], v[124:125], 0.5, v[136:137] op_sel_hi:[1,0,1]
	v_pk_fma_f32 v[122:123], v[122:123], 0.5, v[146:147] op_sel_hi:[1,0,1]
	v_pk_fma_f32 v[128:129], v[128:129], 0.5, v[138:139] op_sel_hi:[1,0,1]
	v_pk_fma_f32 v[126:127], v[126:127], 0.5, v[148:149] op_sel_hi:[1,0,1]
	v_pk_fma_f32 v[104:105], v[104:105], 0.5, v[140:141] op_sel_hi:[1,0,1]
	v_pk_fma_f32 v[102:103], v[102:103], 0.5, v[152:153] op_sel_hi:[1,0,1]
	v_pk_fma_f32 v[112:113], v[112:113], 0.5, v[142:143] op_sel_hi:[1,0,1]
	v_pk_fma_f32 v[110:111], v[110:111], 0.5, v[154:155] op_sel_hi:[1,0,1]
	s_nop 0
	v_add_u32_e32 v144, 0x90, v132
	v_ashrrev_i32_e32 v145, 31, v144
	v_lshlrev_b64 v[144:145], 11, v[144:145]
	v_lshl_add_u64 v[144:145], s[10:11], 0, v[144:145]
	v_lshl_add_u64 v[144:145], v[144:145], 0, v[134:135]
	s_waitcnt vmcnt(7)
	v_lshlrev_b32_e32 v146, 16, v208
	v_and_b32_e32 v147, 0xffff0000, v208
	v_lshlrev_b32_e32 v136, 16, v209
	v_and_b32_e32 v137, 0xffff0000, v209
	v_lshlrev_b32_e32 v148, 16, v210
	v_and_b32_e32 v149, 0xffff0000, v210
	v_lshlrev_b32_e32 v138, 16, v211
	v_and_b32_e32 v139, 0xffff0000, v211
	s_waitcnt vmcnt(6)
	v_lshlrev_b32_e32 v152, 16, v212
	v_and_b32_e32 v153, 0xffff0000, v212
	v_lshlrev_b32_e32 v140, 16, v213
	v_and_b32_e32 v141, 0xffff0000, v213
	v_lshlrev_b32_e32 v154, 16, v214
	v_and_b32_e32 v155, 0xffff0000, v214
	v_lshlrev_b32_e32 v142, 16, v215
	v_and_b32_e32 v143, 0xffff0000, v215
	v_pk_mul_f32 v[146:147], v[146:147], s[0:1] op_sel_hi:[1,0]
	v_pk_mul_f32 v[136:137], v[136:137], s[0:1] op_sel_hi:[1,0]
	v_pk_mul_f32 v[148:149], v[148:149], s[0:1] op_sel_hi:[1,0]
	v_pk_mul_f32 v[138:139], v[138:139], s[0:1] op_sel_hi:[1,0]
	v_pk_mul_f32 v[152:153], v[152:153], s[0:1] op_sel_hi:[1,0]
	v_pk_mul_f32 v[140:141], v[140:141], s[0:1] op_sel_hi:[1,0]
	v_pk_mul_f32 v[154:155], v[154:155], s[0:1] op_sel_hi:[1,0]
	v_pk_mul_f32 v[142:143], v[142:143], s[0:1] op_sel_hi:[1,0]
	v_pk_fma_f32 v[64:65], v[64:65], 0.5, v[136:137] op_sel_hi:[1,0,1]
	v_pk_fma_f32 v[62:63], v[62:63], 0.5, v[146:147] op_sel_hi:[1,0,1]
	v_pk_fma_f32 v[60:61], v[60:61], 0.5, v[138:139] op_sel_hi:[1,0,1]
	v_pk_fma_f32 v[58:59], v[58:59], 0.5, v[148:149] op_sel_hi:[1,0,1]
	v_pk_fma_f32 v[56:57], v[56:57], 0.5, v[140:141] op_sel_hi:[1,0,1]
	v_pk_fma_f32 v[54:55], v[54:55], 0.5, v[152:153] op_sel_hi:[1,0,1]
	v_pk_fma_f32 v[52:53], v[52:53], 0.5, v[142:143] op_sel_hi:[1,0,1]
	v_pk_fma_f32 v[50:51], v[50:51], 0.5, v[154:155] op_sel_hi:[1,0,1]
	s_nop 0
	v_add_u32_e32 v144, 0xa0, v132
	v_ashrrev_i32_e32 v145, 31, v144
	v_lshlrev_b64 v[144:145], 11, v[144:145]
	v_lshl_add_u64 v[144:145], s[10:11], 0, v[144:145]
	v_lshl_add_u64 v[144:145], v[144:145], 0, v[134:135]
	v_add_u32_e32 v132, 0xb0, v132
	v_ashrrev_i32_e32 v133, 31, v132
	v_lshlrev_b64 v[132:133], 11, v[132:133]
	v_lshl_add_u64 v[132:133], s[10:11], 0, v[132:133]
	v_lshl_add_u64 v[132:133], v[132:133], 0, v[134:135]
	v_mov_b32_e32 v134, v71
	v_mov_b32_e32 v135, v72
	s_waitcnt vmcnt(5)
;     __device__ __forceinline__ bool run(const f32x4 (&v)[2][2][4][2], const Unit& u, int wr, int wc, int fr, int fq, PG8_LAS unsigned char* lds, int wid, int lane) const {
;     ...
;                     for (int n = 0; n < 2; ++n) { const f32x4 x = v[ai][bj][m][n]; s += (x[0] + x[1]) + (x[2] + x[3]); }
;                 s += __shfl_xor(s, 16); s += __shfl_xor(s, 32);
;     __device__ __forceinline__ void fused(f32x4 (&acc)[2][2][4][2], const Unit& u, int wr, int wc, int fr, int fq, PG8_LAS unsigned char* lds, int wid, int lane) const {
;     ...
;             for (int m = 0; m < 4; ++m) { const size_t off = (size_t)(u.pm * BM + ai * HALF + wr * 64 + m * 16 + fr) * ldc + col0;
; #pragma unroll
;                 for (int bj = 0; bj < 2; ++bj) { f32x4 b0, b1;
;                     if (base) { b0 = *(const f32x4*)(base + off + bj * HALF); b1 = *(const f32x4*)(base + off + bj * HALF + 4); }
;                     else { const u32x4 w = *(const u32x4*)(baseb + off + bj * HALF);
;                         b0 = (f32x4){__uint_as_float(w.x << 16), __uint_as_float(w.x & 0xffff0000u), __uint_as_float(w.y << 16), __uint_as_float(w.y & 0xffff0000u)};
;                         b1 = (f32x4){__uint_as_float(w.z << 16), __uint_as_float(w.z & 0xffff0000u), __uint_as_float(w.w << 16), __uint_as_float(w.w & 0xffff0000u)}; }
;                     acc[ai][bj][m][0] = acc[ai][bj][m][0] * s + b0 * alpha; acc[ai][bj][m][1] = acc[ai][bj][m][1] * s + b1 * alpha; }
	v_lshlrev_b32_e32 v146, 16, v216
	v_and_b32_e32 v147, 0xffff0000, v216
	v_lshlrev_b32_e32 v136, 16, v217
	v_and_b32_e32 v137, 0xffff0000, v217
	v_lshlrev_b32_e32 v148, 16, v218
	v_and_b32_e32 v149, 0xffff0000, v218
	v_lshlrev_b32_e32 v138, 16, v219
	v_and_b32_e32 v139, 0xffff0000, v219
	s_waitcnt vmcnt(4)
	v_lshlrev_b32_e32 v152, 16, v220
	v_and_b32_e32 v153, 0xffff0000, v220
	v_lshlrev_b32_e32 v140, 16, v221
	v_and_b32_e32 v141, 0xffff0000, v221
	v_lshlrev_b32_e32 v154, 16, v222
	v_and_b32_e32 v155, 0xffff0000, v222
	v_lshlrev_b32_e32 v142, 16, v223
	v_and_b32_e32 v143, 0xffff0000, v223
	v_pk_mul_f32 v[146:147], v[146:147], s[0:1] op_sel_hi:[1,0]
	v_pk_mul_f32 v[136:137], v[136:137], s[0:1] op_sel_hi:[1,0]
	v_pk_mul_f32 v[148:149], v[148:149], s[0:1] op_sel_hi:[1,0]
	v_pk_mul_f32 v[138:139], v[138:139], s[0:1] op_sel_hi:[1,0]
	v_pk_mul_f32 v[152:153], v[152:153], s[0:1] op_sel_hi:[1,0]
	v_pk_mul_f32 v[140:141], v[140:141], s[0:1] op_sel_hi:[1,0]
	v_pk_mul_f32 v[154:155], v[154:155], s[0:1] op_sel_hi:[1,0]
	v_pk_mul_f32 v[142:143], v[142:143], s[0:1] op_sel_hi:[1,0]
	v_pk_fma_f32 v[48:49], v[48:49], 0.5, v[136:137] op_sel_hi:[1,0,1]
	v_pk_fma_f32 v[46:47], v[46:47], 0.5, v[146:147] op_sel_hi:[1,0,1]
	v_pk_fma_f32 v[44:45], v[44:45], 0.5, v[138:139] op_sel_hi:[1,0,1]
	v_pk_fma_f32 v[42:43], v[42:43], 0.5, v[148:149] op_sel_hi:[1,0,1]
	v_pk_fma_f32 v[40:41], v[40:41], 0.5, v[140:141] op_sel_hi:[1,0,1]
	v_pk_fma_f32 v[38:39], v[38:39], 0.5, v[152:153] op_sel_hi:[1,0,1]
	v_pk_fma_f32 v[36:37], v[36:37], 0.5, v[142:143] op_sel_hi:[1,0,1]
	v_pk_fma_f32 v[34:35], v[34:35], 0.5, v[154:155] op_sel_hi:[1,0,1]
	v_mov_b32_e32 v146, v70
	v_mov_b32_e32 v147, v73
	v_pk_add_f32 v[134:135], v[134:135], v[146:147]
	s_waitcnt vmcnt(3)
	v_lshlrev_b32_e32 v144, 16, v224
	v_and_b32_e32 v145, 0xffff0000, v224
	v_lshlrev_b32_e32 v136, 16, v225
	v_and_b32_e32 v137, 0xffff0000, v225
	v_lshlrev_b32_e32 v148, 16, v226
	v_and_b32_e32 v149, 0xffff0000, v226
	v_lshlrev_b32_e32 v138, 16, v227
	v_and_b32_e32 v139, 0xffff0000, v227
	s_waitcnt vmcnt(2)
	v_lshlrev_b32_e32 v152, 16, v228
	v_and_b32_e32 v153, 0xffff0000, v228
	v_lshlrev_b32_e32 v140, 16, v229
	v_and_b32_e32 v141, 0xffff0000, v229
	v_lshlrev_b32_e32 v154, 16, v230
	v_and_b32_e32 v155, 0xffff0000, v230
	v_lshlrev_b32_e32 v142, 16, v231
	v_and_b32_e32 v143, 0xffff0000, v231
	v_pk_mul_f32 v[144:145], v[144:145], s[0:1] op_sel_hi:[1,0]
	v_pk_mul_f32 v[136:137], v[136:137], s[0:1] op_sel_hi:[1,0]
	v_pk_mul_f32 v[148:149], v[148:149], s[0:1] op_sel_hi:[1,0]
	v_pk_mul_f32 v[138:139], v[138:139], s[0:1] op_sel_hi:[1,0]
	v_pk_mul_f32 v[152:153], v[152:153], s[0:1] op_sel_hi:[1,0]
	v_pk_mul_f32 v[140:141], v[140:141], s[0:1] op_sel_hi:[1,0]
	v_pk_mul_f32 v[154:155], v[154:155], s[0:1] op_sel_hi:[1,0]
	v_pk_mul_f32 v[142:143], v[142:143], s[0:1] op_sel_hi:[1,0]
	v_pk_fma_f32 v[32:33], v[32:33], 0.5, v[136:137] op_sel_hi:[1,0,1]
	v_pk_fma_f32 v[30:31], v[30:31], 0.5, v[144:145] op_sel_hi:[1,0,1]
	v_pk_fma_f32 v[28:29], v[28:29], 0.5, v[138:139] op_sel_hi:[1,0,1]
	v_pk_fma_f32 v[26:27], v[26:27], 0.5, v[148:149] op_sel_hi:[1,0,1]
	v_pk_fma_f32 v[24:25], v[24:25], 0.5, v[140:141] op_sel_hi:[1,0,1]
	v_pk_fma_f32 v[22:23], v[22:23], 0.5, v[152:153] op_sel_hi:[1,0,1]
	v_pk_fma_f32 v[20:21], v[20:21], 0.5, v[142:143] op_sel_hi:[1,0,1]
	v_pk_fma_f32 v[18:19], v[18:19], 0.5, v[154:155] op_sel_hi:[1,0,1]
	v_mov_b32_e32 v136, v79
	v_mov_b32_e32 v137, v80
	v_mov_b32_e32 v148, v78
	v_mov_b32_e32 v149, v81
	v_pk_add_f32 v[136:137], v[136:137], v[148:149]
	v_add_f32_e32 v133, v134, v135
	v_pk_add_f32 v[134:135], v[136:137], v[136:137] op_sel_hi:[0,1]
	v_add_f32_e32 v153, v66, v67
	v_add_f32_e32 v155, v68, v69
	v_mov_b32_e32 v152, v74
	v_mov_b32_e32 v154, v75
	v_mov_b32_e32 v132, v77
	v_add_f32_e32 v133, 0, v133
	v_mov_b32_e32 v134, v76
	v_pk_add_f32 v[146:147], v[152:153], v[154:155]
	v_pk_add_f32 v[132:133], v[134:135], v[132:133]
	s_nop 0
	v_pk_add_f32 v[132:133], v[146:147], v[132:133]
	s_nop 0
	v_add_f32_e32 v133, v132, v133
	v_mov_b32_e32 v134, v133
	s_nop 1
	v_permlane16_swap_b32 v133, v134
	v_xor_b32_e32 v132, 32, v156
	v_cmp_lt_i32_e32 vcc, v132, v157
	s_waitcnt lgkmcnt(0)
;     __device__ __forceinline__ bool run(const f32x4 (&v)[2][2][4][2], const Unit& u, int wr, int wc, int fr, int fq, PG8_LAS unsigned char* lds, int wid, int lane) const {
;     ...
;                     for (int n = 0; n < 2; ++n) { const f32x4 x = v[ai][bj][m][n]; s += (x[0] + x[1]) + (x[2] + x[3]); }
;                 s += __shfl_xor(s, 16); s += __shfl_xor(s, 32);
;                 const float mw = s * (1.0f / 64.0f); float q = 0.f;
; #pragma unroll
;                 for (int bj = 0; bj < 2; ++bj)
; #pragma unroll
;                     for (int n = 0; n < 2; ++n) { const f32x4 d = v[ai][bj][m][n] - mw; q += (d[0] * d[0] + d[1] * d[1]) + (d[2] * d[2] + d[3] * d[3]); }
;                 q += __shfl_xor(q, 16); q += __shfl_xor(q, 32);
;                 if (fq == 0) P[(ai * HALF + wr * 64 + m * 16 + fr) * 4 + wc] = (f32x2v){mw, q};
	v_add_f32_e32 v133, v133, v134
	v_cndmask_b32_e32 v132, v156, v132, vcc
	v_lshlrev_b32_e32 v132, 2, v132
	v_mov_b32_e32 v134, v133
	s_nop 1
	v_permlane32_swap_b32 v133, v134
	s_waitcnt lgkmcnt(0)
	v_add_f32_e32 v133, v133, v134
	v_fmamk_f32 v135, v133, 0xbc800000, v73
	v_fmamk_f32 v137, v133, 0xbc800000, v71
	v_fmamk_f32 v147, v133, 0xbc800000, v81
	v_fmamk_f32 v149, v133, 0xbc800000, v79
	v_fmamk_f32 v134, v133, 0xbc800000, v72
	v_fmamk_f32 v136, v133, 0xbc800000, v70
	v_fmamk_f32 v146, v133, 0xbc800000, v80
	v_fmamk_f32 v148, v133, 0xbc800000, v78
	v_fmamk_f32 v153, v133, 0xbc800000, v69
	v_fmamk_f32 v155, v133, 0xbc800000, v67
	v_mul_f32_e32 v137, v137, v137
	v_mul_f32_e32 v135, v135, v135
	v_mul_f32_e32 v149, v149, v149
	v_mul_f32_e32 v147, v147, v147
	v_fmamk_f32 v152, v133, 0xbc800000, v68
	v_fmamk_f32 v154, v133, 0xbc800000, v66
	v_fmamk_f32 v157, v133, 0xbc800000, v77
	v_fmamk_f32 v159, v133, 0xbc800000, v75
	v_mul_f32_e32 v155, v155, v155
	v_mul_f32_e32 v153, v153, v153
	v_fmac_f32_e32 v137, v136, v136
	v_fmac_f32_e32 v135, v134, v134
	v_fmac_f32_e32 v149, v148, v148
	v_fmac_f32_e32 v147, v146, v146
	v_fmamk_f32 v156, v133, 0xbc800000, v76
	v_fmamk_f32 v158, v133, 0xbc800000, v74
	v_mul_f32_e32 v159, v159, v159
	v_mul_f32_e32 v157, v157, v157
	v_fmac_f32_e32 v155, v154, v154
	v_fmac_f32_e32 v153, v152, v152
	v_add_f32_e32 v134, v137, v135
	v_add_f32_e32 v135, v149, v147
	v_fmac_f32_e32 v159, v158, v158
	v_fmac_f32_e32 v157, v156, v156
	v_add_f32_e32 v136, v155, v153
	v_add_f32_e32 v134, v134, v135
	v_add_f32_e32 v137, v159, v157
	v_add_f32_e32 v134, v136, v134
	v_add_f32_e32 v135, v137, v134
	v_mov_b32_e32 v136, v135
	s_nop 1
	v_permlane16_swap_b32 v135, v136
	v_and_b32_e32 v134, 63, v150
	v_cmp_gt_u32_e32 vcc, 16, v134
	s_waitcnt lgkmcnt(0)
	v_add_f32_e32 v135, v135, v136
	s_waitcnt vmcnt(1)
	v_lshlrev_b32_e32 v146, 16, v232
	v_and_b32_e32 v147, 0xffff0000, v232
	v_lshlrev_b32_e32 v138, 16, v233
	v_and_b32_e32 v139, 0xffff0000, v233
	v_lshlrev_b32_e32 v148, 16, v234
	v_and_b32_e32 v149, 0xffff0000, v234
	v_lshlrev_b32_e32 v140, 16, v235
	v_and_b32_e32 v141, 0xffff0000, v235
	s_waitcnt vmcnt(0)
	v_lshlrev_b32_e32 v152, 16, v236
	v_and_b32_e32 v153, 0xffff0000, v236
	v_lshlrev_b32_e32 v142, 16, v237
	v_and_b32_e32 v143, 0xffff0000, v237
	v_lshlrev_b32_e32 v154, 16, v238
	v_and_b32_e32 v155, 0xffff0000, v238
	v_lshlrev_b32_e32 v144, 16, v239
	v_and_b32_e32 v145, 0xffff0000, v239
	v_mov_b32_e32 v136, v135
	s_nop 1
	v_permlane32_swap_b32 v135, v136
	v_pk_mul_f32 v[146:147], v[146:147], s[0:1] op_sel_hi:[1,0]
	v_pk_mul_f32 v[138:139], v[138:139], s[0:1] op_sel_hi:[1,0]
	v_pk_mul_f32 v[148:149], v[148:149], s[0:1] op_sel_hi:[1,0]
	v_pk_mul_f32 v[140:141], v[140:141], s[0:1] op_sel_hi:[1,0]
	v_pk_mul_f32 v[152:153], v[152:153], s[0:1] op_sel_hi:[1,0]
	v_pk_mul_f32 v[142:143], v[142:143], s[0:1] op_sel_hi:[1,0]
	v_pk_mul_f32 v[154:155], v[154:155], s[0:1] op_sel_hi:[1,0]
	v_pk_mul_f32 v[144:145], v[144:145], s[0:1] op_sel_hi:[1,0]
	v_pk_fma_f32 v[16:17], v[16:17], 0.5, v[138:139] op_sel_hi:[1,0,1]
	v_pk_fma_f32 v[14:15], v[14:15], 0.5, v[146:147] op_sel_hi:[1,0,1]
	v_pk_fma_f32 v[12:13], v[12:13], 0.5, v[140:141] op_sel_hi:[1,0,1]
	v_pk_fma_f32 v[10:11], v[10:11], 0.5, v[148:149] op_sel_hi:[1,0,1]
	v_pk_fma_f32 v[8:9], v[8:9], 0.5, v[142:143] op_sel_hi:[1,0,1]
	v_pk_fma_f32 v[6:7], v[6:7], 0.5, v[152:153] op_sel_hi:[1,0,1]
	v_pk_fma_f32 v[4:5], v[4:5], 0.5, v[144:145] op_sel_hi:[1,0,1]
	v_pk_fma_f32 v[2:3], v[2:3], 0.5, v[154:155] op_sel_hi:[1,0,1]
	s_lshl_b32 s0, s27, 3
	s_add_i32 s2, s0, 0
	s_and_saveexec_b64 s[0:1], vcc
	s_cbranch_execz .LBB0_1715
	s_lshl_b32 s3, s26, 11
	s_add_i32 s3, s2, s3
	v_mul_f32_e32 v138, 0x3c800000, v133
	v_lshl_add_u32 v133, v151, 5, s3
	s_waitcnt lgkmcnt(0)
	v_add_f32_e32 v139, v135, v136
	ds_write_b64 v133, v[138:139]
